# scan: decay table in 5 VGPRs + v_readlane SGPR operand (half the loads), chunk loads 31 ahead, fully unrolled
# speedup vs baseline: 1.0057x; 1.0055x over previous
; DI int ltid() { int t = threadIdx.x & 255; asm volatile("" : "+v"(t)); return t; }
; DI void scan_item(const Params& p, int it) {
;   const int chain = it >> 4, e = (it & 15) * 256 + ltid(), k = e >> 6;
;   float* L = p.HL + (size_t)chain * NCHUNK * 4096 + e;
;   const float* dc = p.Hdec + chain * NCHUNK * 64 + k;
;   float S = 0.f;
;   for (int n0 = 0; n0 < NCHUNK; n0 += 26) {
;     float l[26], dd[26];
; #pragma unroll
;     for (int j = 0; j < 26; ++j) { l[j] = L[(size_t)(n0 + j) * 4096]; dd[j] = dc[(n0 + j) * 64]; }
; #pragma unroll
;     for (int j = 0; j < 26; ++j) { L[(size_t)(n0 + j) * 4096] = S; S = dd[j] * S + l[j]; }
;   }
.LBB0_434:
	s_mov_b32 s24, 0x4000
	s_mov_b32 s25, 0
	v_add_co_u32_e32 v4, vcc, 0xfff9c000, v2
	s_nop 1
	v_addc_co_u32_e32 v5, vcc, -1, v3, vcc
	v_add_co_u32_e32 v8, vcc, 0xffffe700, v0
	s_nop 1
	v_addc_co_u32_e32 v9, vcc, -1, v1, vcc
	v_lshlrev_b32_e32 v67, 8, v216
	v_mov_b32_e32 v6, v4
	v_mov_b32_e32 v7, v5
	v_add_co_u32_e32 v60, vcc, v8, v67
	s_nop 1
	v_addc_co_u32_e32 v61, vcc, 0, v9, vcc
	global_load_dword v62, v[60:61], off
	v_lshl_add_u64 v[60:61], v[60:61], 0, s[24:25]
	global_load_dword v63, v[60:61], off
	v_lshl_add_u64 v[60:61], v[60:61], 0, s[24:25]
	global_load_dword v64, v[60:61], off
	v_lshl_add_u64 v[60:61], v[60:61], 0, s[24:25]
	global_load_dword v65, v[60:61], off
	v_lshl_add_u64 v[60:61], v[60:61], 0, s[24:25]
	s_mov_b64 s[42:43], exec
	s_mov_b64 exec, 15
	s_nop 0
	global_load_dword v66, v[60:61], off
	s_mov_b64 exec, s[42:43]
	global_load_dword v20, v[4:5], off
	v_lshl_add_u64 v[4:5], v[4:5], 0, s[24:25]
	global_load_dword v21, v[4:5], off
	v_lshl_add_u64 v[4:5], v[4:5], 0, s[24:25]
	global_load_dword v22, v[4:5], off
	v_lshl_add_u64 v[4:5], v[4:5], 0, s[24:25]
	global_load_dword v23, v[4:5], off
	v_lshl_add_u64 v[4:5], v[4:5], 0, s[24:25]
	global_load_dword v24, v[4:5], off
	v_lshl_add_u64 v[4:5], v[4:5], 0, s[24:25]
	global_load_dword v25, v[4:5], off
	v_lshl_add_u64 v[4:5], v[4:5], 0, s[24:25]
	global_load_dword v26, v[4:5], off
	v_lshl_add_u64 v[4:5], v[4:5], 0, s[24:25]
	global_load_dword v27, v[4:5], off
	v_lshl_add_u64 v[4:5], v[4:5], 0, s[24:25]
	global_load_dword v28, v[4:5], off
	v_lshl_add_u64 v[4:5], v[4:5], 0, s[24:25]
	global_load_dword v29, v[4:5], off
	v_lshl_add_u64 v[4:5], v[4:5], 0, s[24:25]
	global_load_dword v30, v[4:5], off
	v_lshl_add_u64 v[4:5], v[4:5], 0, s[24:25]
	global_load_dword v31, v[4:5], off
	v_lshl_add_u64 v[4:5], v[4:5], 0, s[24:25]
	global_load_dword v32, v[4:5], off
	v_lshl_add_u64 v[4:5], v[4:5], 0, s[24:25]
	global_load_dword v33, v[4:5], off
	v_lshl_add_u64 v[4:5], v[4:5], 0, s[24:25]
	global_load_dword v34, v[4:5], off
	v_lshl_add_u64 v[4:5], v[4:5], 0, s[24:25]
	global_load_dword v35, v[4:5], off
	v_lshl_add_u64 v[4:5], v[4:5], 0, s[24:25]
	global_load_dword v36, v[4:5], off
	v_lshl_add_u64 v[4:5], v[4:5], 0, s[24:25]
	global_load_dword v37, v[4:5], off
	v_lshl_add_u64 v[4:5], v[4:5], 0, s[24:25]
	global_load_dword v38, v[4:5], off
	v_lshl_add_u64 v[4:5], v[4:5], 0, s[24:25]
	global_load_dword v39, v[4:5], off
	v_lshl_add_u64 v[4:5], v[4:5], 0, s[24:25]
	global_load_dword v40, v[4:5], off
	v_lshl_add_u64 v[4:5], v[4:5], 0, s[24:25]
	global_load_dword v41, v[4:5], off
	v_lshl_add_u64 v[4:5], v[4:5], 0, s[24:25]
	global_load_dword v42, v[4:5], off
	v_lshl_add_u64 v[4:5], v[4:5], 0, s[24:25]
	global_load_dword v43, v[4:5], off
	v_lshl_add_u64 v[4:5], v[4:5], 0, s[24:25]
	global_load_dword v44, v[4:5], off
	v_lshl_add_u64 v[4:5], v[4:5], 0, s[24:25]
	global_load_dword v45, v[4:5], off
	v_lshl_add_u64 v[4:5], v[4:5], 0, s[24:25]
	global_load_dword v46, v[4:5], off
	v_lshl_add_u64 v[4:5], v[4:5], 0, s[24:25]
	global_load_dword v47, v[4:5], off
	v_lshl_add_u64 v[4:5], v[4:5], 0, s[24:25]
	global_load_dword v48, v[4:5], off
	v_lshl_add_u64 v[4:5], v[4:5], 0, s[24:25]
	global_load_dword v49, v[4:5], off
	v_lshl_add_u64 v[4:5], v[4:5], 0, s[24:25]
	global_load_dword v50, v[4:5], off
	v_lshl_add_u64 v[4:5], v[4:5], 0, s[24:25]
	s_waitcnt vmcnt(31)
	v_readlane_b32 s3, v62, 0
	v_readlane_b32 s22, v62, 1
	global_load_dword v51, v[4:5], off
	v_lshl_add_u64 v[4:5], v[4:5], 0, s[24:25]
	s_waitcnt vmcnt(31)
	global_store_dword v[6:7], v18, off
	v_fmac_f32_e32 v20, s3, v18
	v_lshl_add_u64 v[6:7], v[6:7], 0, s[24:25]
	v_readlane_b32 s26, v62, 2
	global_load_dword v52, v[4:5], off
	v_lshl_add_u64 v[4:5], v[4:5], 0, s[24:25]
	s_waitcnt vmcnt(32)
	global_store_dword v[6:7], v20, off
	v_fmac_f32_e32 v21, s22, v20
	v_lshl_add_u64 v[6:7], v[6:7], 0, s[24:25]
	v_readlane_b32 s32, v62, 3
	global_load_dword v53, v[4:5], off
	v_lshl_add_u64 v[4:5], v[4:5], 0, s[24:25]
	s_waitcnt vmcnt(33)
	global_store_dword v[6:7], v21, off
	v_fmac_f32_e32 v22, s26, v21
	v_lshl_add_u64 v[6:7], v[6:7], 0, s[24:25]
	v_readlane_b32 s3, v62, 4
	global_load_dword v54, v[4:5], off
	v_lshl_add_u64 v[4:5], v[4:5], 0, s[24:25]
	s_waitcnt vmcnt(34)
	global_store_dword v[6:7], v22, off
	v_fmac_f32_e32 v23, s32, v22
	v_lshl_add_u64 v[6:7], v[6:7], 0, s[24:25]
	v_readlane_b32 s22, v62, 5
	global_load_dword v55, v[4:5], off
	v_lshl_add_u64 v[4:5], v[4:5], 0, s[24:25]
	s_waitcnt vmcnt(35)
	global_store_dword v[6:7], v23, off
	v_fmac_f32_e32 v24, s3, v23
	v_lshl_add_u64 v[6:7], v[6:7], 0, s[24:25]
	v_readlane_b32 s26, v62, 6
	global_load_dword v56, v[4:5], off
	v_lshl_add_u64 v[4:5], v[4:5], 0, s[24:25]
	s_waitcnt vmcnt(36)
	global_store_dword v[6:7], v24, off
	v_fmac_f32_e32 v25, s22, v24
	v_lshl_add_u64 v[6:7], v[6:7], 0, s[24:25]
	v_readlane_b32 s32, v62, 7
	global_load_dword v57, v[4:5], off
	v_lshl_add_u64 v[4:5], v[4:5], 0, s[24:25]
	s_waitcnt vmcnt(37)
	global_store_dword v[6:7], v25, off
	v_fmac_f32_e32 v26, s26, v25
	v_lshl_add_u64 v[6:7], v[6:7], 0, s[24:25]
	v_readlane_b32 s3, v62, 8
	global_load_dword v58, v[4:5], off
	v_lshl_add_u64 v[4:5], v[4:5], 0, s[24:25]
	s_waitcnt vmcnt(38)
	global_store_dword v[6:7], v26, off
	v_fmac_f32_e32 v27, s32, v26
	v_lshl_add_u64 v[6:7], v[6:7], 0, s[24:25]
	v_readlane_b32 s22, v62, 9
	global_load_dword v59, v[4:5], off
	v_lshl_add_u64 v[4:5], v[4:5], 0, s[24:25]
	s_waitcnt vmcnt(39)
	global_store_dword v[6:7], v27, off
	v_fmac_f32_e32 v28, s3, v27
	v_lshl_add_u64 v[6:7], v[6:7], 0, s[24:25]
	v_readlane_b32 s26, v62, 10
	global_load_dword v20, v[4:5], off
	v_lshl_add_u64 v[4:5], v[4:5], 0, s[24:25]
	s_waitcnt vmcnt(40)
; DI void scan_item(const Params& p, int it) {
;     ...
;   for (int n0 = 0; n0 < NCHUNK; n0 += 26) {
;     float l[26], dd[26];
; #pragma unroll
;     for (int j = 0; j < 26; ++j) { l[j] = L[(size_t)(n0 + j) * 4096]; dd[j] = dc[(n0 + j) * 64]; }
; #pragma unroll
;     for (int j = 0; j < 26; ++j) { L[(size_t)(n0 + j) * 4096] = S; S = dd[j] * S + l[j]; }
;   }
	global_store_dword v[6:7], v28, off
	v_fmac_f32_e32 v29, s22, v28
	v_lshl_add_u64 v[6:7], v[6:7], 0, s[24:25]
	v_readlane_b32 s32, v62, 11
	global_load_dword v21, v[4:5], off
	v_lshl_add_u64 v[4:5], v[4:5], 0, s[24:25]
	s_waitcnt vmcnt(41)
	global_store_dword v[6:7], v29, off
	v_fmac_f32_e32 v30, s26, v29
	v_lshl_add_u64 v[6:7], v[6:7], 0, s[24:25]
	v_readlane_b32 s3, v62, 12
	global_load_dword v22, v[4:5], off
	v_lshl_add_u64 v[4:5], v[4:5], 0, s[24:25]
	s_waitcnt vmcnt(42)
	global_store_dword v[6:7], v30, off
	v_fmac_f32_e32 v31, s32, v30
	v_lshl_add_u64 v[6:7], v[6:7], 0, s[24:25]
	v_readlane_b32 s22, v62, 13
	global_load_dword v23, v[4:5], off
	v_lshl_add_u64 v[4:5], v[4:5], 0, s[24:25]
	s_waitcnt vmcnt(43)
	global_store_dword v[6:7], v31, off
	v_fmac_f32_e32 v32, s3, v31
	v_lshl_add_u64 v[6:7], v[6:7], 0, s[24:25]
	v_readlane_b32 s26, v62, 14
	global_load_dword v24, v[4:5], off
	v_lshl_add_u64 v[4:5], v[4:5], 0, s[24:25]
	s_waitcnt vmcnt(44)
	global_store_dword v[6:7], v32, off
	v_fmac_f32_e32 v33, s22, v32
	v_lshl_add_u64 v[6:7], v[6:7], 0, s[24:25]
	v_readlane_b32 s32, v62, 15
	global_load_dword v25, v[4:5], off
	v_lshl_add_u64 v[4:5], v[4:5], 0, s[24:25]
	s_waitcnt vmcnt(45)
	global_store_dword v[6:7], v33, off
	v_fmac_f32_e32 v34, s26, v33
	v_lshl_add_u64 v[6:7], v[6:7], 0, s[24:25]
	v_readlane_b32 s3, v62, 16
	global_load_dword v26, v[4:5], off
	v_lshl_add_u64 v[4:5], v[4:5], 0, s[24:25]
	s_waitcnt vmcnt(46)
	global_store_dword v[6:7], v34, off
	v_fmac_f32_e32 v35, s32, v34
	v_lshl_add_u64 v[6:7], v[6:7], 0, s[24:25]
	v_readlane_b32 s22, v62, 17
	global_load_dword v27, v[4:5], off
	v_lshl_add_u64 v[4:5], v[4:5], 0, s[24:25]
	s_waitcnt vmcnt(47)
	global_store_dword v[6:7], v35, off
	v_fmac_f32_e32 v36, s3, v35
	v_lshl_add_u64 v[6:7], v[6:7], 0, s[24:25]
	v_readlane_b32 s26, v62, 18
	global_load_dword v28, v[4:5], off
	v_lshl_add_u64 v[4:5], v[4:5], 0, s[24:25]
	s_waitcnt vmcnt(48)
	global_store_dword v[6:7], v36, off
	v_fmac_f32_e32 v37, s22, v36
	v_lshl_add_u64 v[6:7], v[6:7], 0, s[24:25]
	v_readlane_b32 s32, v62, 19
	global_load_dword v29, v[4:5], off
	v_lshl_add_u64 v[4:5], v[4:5], 0, s[24:25]
	s_waitcnt vmcnt(49)
	global_store_dword v[6:7], v37, off
	v_fmac_f32_e32 v38, s26, v37
	v_lshl_add_u64 v[6:7], v[6:7], 0, s[24:25]
	v_readlane_b32 s3, v62, 20
	global_load_dword v30, v[4:5], off
	v_lshl_add_u64 v[4:5], v[4:5], 0, s[24:25]
	s_waitcnt vmcnt(50)
	global_store_dword v[6:7], v38, off
	v_fmac_f32_e32 v39, s32, v38
	v_lshl_add_u64 v[6:7], v[6:7], 0, s[24:25]
	v_readlane_b32 s22, v62, 21
	global_load_dword v31, v[4:5], off
	v_lshl_add_u64 v[4:5], v[4:5], 0, s[24:25]
	s_waitcnt vmcnt(51)
	global_store_dword v[6:7], v39, off
	v_fmac_f32_e32 v40, s3, v39
	v_lshl_add_u64 v[6:7], v[6:7], 0, s[24:25]
	v_readlane_b32 s26, v62, 22
	global_load_dword v32, v[4:5], off
	v_lshl_add_u64 v[4:5], v[4:5], 0, s[24:25]
	s_waitcnt vmcnt(52)
	global_store_dword v[6:7], v40, off
	v_fmac_f32_e32 v41, s22, v40
	v_lshl_add_u64 v[6:7], v[6:7], 0, s[24:25]
	v_readlane_b32 s32, v62, 23
	global_load_dword v33, v[4:5], off
	v_lshl_add_u64 v[4:5], v[4:5], 0, s[24:25]
	s_waitcnt vmcnt(53)
	global_store_dword v[6:7], v41, off
	v_fmac_f32_e32 v42, s26, v41
	v_lshl_add_u64 v[6:7], v[6:7], 0, s[24:25]
	v_readlane_b32 s3, v62, 24
	global_load_dword v34, v[4:5], off
	v_lshl_add_u64 v[4:5], v[4:5], 0, s[24:25]
	s_waitcnt vmcnt(54)
	global_store_dword v[6:7], v42, off
	v_fmac_f32_e32 v43, s32, v42
	v_lshl_add_u64 v[6:7], v[6:7], 0, s[24:25]
	v_readlane_b32 s22, v62, 25
	global_load_dword v35, v[4:5], off
	v_lshl_add_u64 v[4:5], v[4:5], 0, s[24:25]
	s_waitcnt vmcnt(55)
	global_store_dword v[6:7], v43, off
	v_fmac_f32_e32 v44, s3, v43
	v_lshl_add_u64 v[6:7], v[6:7], 0, s[24:25]
	v_readlane_b32 s26, v62, 26
	global_load_dword v36, v[4:5], off
	v_lshl_add_u64 v[4:5], v[4:5], 0, s[24:25]
	s_waitcnt vmcnt(56)
	global_store_dword v[6:7], v44, off
	v_fmac_f32_e32 v45, s22, v44
	v_lshl_add_u64 v[6:7], v[6:7], 0, s[24:25]
	v_readlane_b32 s32, v62, 27
	global_load_dword v37, v[4:5], off
	v_lshl_add_u64 v[4:5], v[4:5], 0, s[24:25]
	s_waitcnt vmcnt(57)
	global_store_dword v[6:7], v45, off
	v_fmac_f32_e32 v46, s26, v45
	v_lshl_add_u64 v[6:7], v[6:7], 0, s[24:25]
	v_readlane_b32 s3, v62, 28
	global_load_dword v38, v[4:5], off
	v_lshl_add_u64 v[4:5], v[4:5], 0, s[24:25]
	s_waitcnt vmcnt(58)
	global_store_dword v[6:7], v46, off
	v_fmac_f32_e32 v47, s32, v46
	v_lshl_add_u64 v[6:7], v[6:7], 0, s[24:25]
	v_readlane_b32 s22, v62, 29
	global_load_dword v39, v[4:5], off
	v_lshl_add_u64 v[4:5], v[4:5], 0, s[24:25]
	s_waitcnt vmcnt(59)
	global_store_dword v[6:7], v47, off
	v_fmac_f32_e32 v48, s3, v47
	v_lshl_add_u64 v[6:7], v[6:7], 0, s[24:25]
	v_readlane_b32 s26, v62, 30
	global_load_dword v40, v[4:5], off
	v_lshl_add_u64 v[4:5], v[4:5], 0, s[24:25]
	s_waitcnt vmcnt(60)
	global_store_dword v[6:7], v48, off
	v_fmac_f32_e32 v49, s22, v48
	v_lshl_add_u64 v[6:7], v[6:7], 0, s[24:25]
	v_readlane_b32 s32, v62, 31
	global_load_dword v41, v[4:5], off
	v_lshl_add_u64 v[4:5], v[4:5], 0, s[24:25]
	s_waitcnt vmcnt(61)
	global_store_dword v[6:7], v49, off
	v_fmac_f32_e32 v50, s26, v49
	v_lshl_add_u64 v[6:7], v[6:7], 0, s[24:25]
	v_readlane_b32 s3, v62, 32
	global_load_dword v42, v[4:5], off
	v_lshl_add_u64 v[4:5], v[4:5], 0, s[24:25]
	s_waitcnt vmcnt(62)
	global_store_dword v[6:7], v50, off
	v_fmac_f32_e32 v51, s32, v50
	v_lshl_add_u64 v[6:7], v[6:7], 0, s[24:25]
	v_readlane_b32 s22, v62, 33
	global_load_dword v43, v[4:5], off
	v_lshl_add_u64 v[4:5], v[4:5], 0, s[24:25]
	s_waitcnt vmcnt(62)
; DI void scan_item(const Params& p, int it) {
;     ...
;   for (int n0 = 0; n0 < NCHUNK; n0 += 26) {
;     float l[26], dd[26];
; #pragma unroll
;     for (int j = 0; j < 26; ++j) { l[j] = L[(size_t)(n0 + j) * 4096]; dd[j] = dc[(n0 + j) * 64]; }
; #pragma unroll
;     for (int j = 0; j < 26; ++j) { L[(size_t)(n0 + j) * 4096] = S; S = dd[j] * S + l[j]; }
;   }
	global_store_dword v[6:7], v51, off
	v_fmac_f32_e32 v52, s3, v51
	v_lshl_add_u64 v[6:7], v[6:7], 0, s[24:25]
	v_readlane_b32 s26, v62, 34
	global_load_dword v44, v[4:5], off
	v_lshl_add_u64 v[4:5], v[4:5], 0, s[24:25]
	s_waitcnt vmcnt(62)
	global_store_dword v[6:7], v52, off
	v_fmac_f32_e32 v53, s22, v52
	v_lshl_add_u64 v[6:7], v[6:7], 0, s[24:25]
	v_readlane_b32 s32, v62, 35
	global_load_dword v45, v[4:5], off
	v_lshl_add_u64 v[4:5], v[4:5], 0, s[24:25]
	s_waitcnt vmcnt(62)
	global_store_dword v[6:7], v53, off
	v_fmac_f32_e32 v54, s26, v53
	v_lshl_add_u64 v[6:7], v[6:7], 0, s[24:25]
	v_readlane_b32 s3, v62, 36
	global_load_dword v46, v[4:5], off
	v_lshl_add_u64 v[4:5], v[4:5], 0, s[24:25]
	s_waitcnt vmcnt(62)
	global_store_dword v[6:7], v54, off
	v_fmac_f32_e32 v55, s32, v54
	v_lshl_add_u64 v[6:7], v[6:7], 0, s[24:25]
	v_readlane_b32 s22, v62, 37
	global_load_dword v47, v[4:5], off
	v_lshl_add_u64 v[4:5], v[4:5], 0, s[24:25]
	s_waitcnt vmcnt(62)
	global_store_dword v[6:7], v55, off
	v_fmac_f32_e32 v56, s3, v55
	v_lshl_add_u64 v[6:7], v[6:7], 0, s[24:25]
	v_readlane_b32 s26, v62, 38
	global_load_dword v48, v[4:5], off
	v_lshl_add_u64 v[4:5], v[4:5], 0, s[24:25]
	s_waitcnt vmcnt(62)
	global_store_dword v[6:7], v56, off
	v_fmac_f32_e32 v57, s22, v56
	v_lshl_add_u64 v[6:7], v[6:7], 0, s[24:25]
	v_readlane_b32 s32, v62, 39
	global_load_dword v49, v[4:5], off
	v_lshl_add_u64 v[4:5], v[4:5], 0, s[24:25]
	s_waitcnt vmcnt(62)
	global_store_dword v[6:7], v57, off
	v_fmac_f32_e32 v58, s26, v57
	v_lshl_add_u64 v[6:7], v[6:7], 0, s[24:25]
	v_readlane_b32 s3, v62, 40
	global_load_dword v50, v[4:5], off
	v_lshl_add_u64 v[4:5], v[4:5], 0, s[24:25]
	s_waitcnt vmcnt(62)
	global_store_dword v[6:7], v58, off
	v_fmac_f32_e32 v59, s32, v58
	v_lshl_add_u64 v[6:7], v[6:7], 0, s[24:25]
	v_readlane_b32 s22, v62, 41
	global_load_dword v51, v[4:5], off
	v_lshl_add_u64 v[4:5], v[4:5], 0, s[24:25]
	s_waitcnt vmcnt(62)
	global_store_dword v[6:7], v59, off
	v_fmac_f32_e32 v20, s3, v59
	v_lshl_add_u64 v[6:7], v[6:7], 0, s[24:25]
	v_readlane_b32 s26, v62, 42
	global_load_dword v52, v[4:5], off
	v_lshl_add_u64 v[4:5], v[4:5], 0, s[24:25]
	s_waitcnt vmcnt(62)
	global_store_dword v[6:7], v20, off
	v_fmac_f32_e32 v21, s22, v20
	v_lshl_add_u64 v[6:7], v[6:7], 0, s[24:25]
	v_readlane_b32 s32, v62, 43
	global_load_dword v53, v[4:5], off
	v_lshl_add_u64 v[4:5], v[4:5], 0, s[24:25]
	s_waitcnt vmcnt(62)
	global_store_dword v[6:7], v21, off
	v_fmac_f32_e32 v22, s26, v21
	v_lshl_add_u64 v[6:7], v[6:7], 0, s[24:25]
	v_readlane_b32 s3, v62, 44
	global_load_dword v54, v[4:5], off
	v_lshl_add_u64 v[4:5], v[4:5], 0, s[24:25]
	s_waitcnt vmcnt(62)
	global_store_dword v[6:7], v22, off
	v_fmac_f32_e32 v23, s32, v22
	v_lshl_add_u64 v[6:7], v[6:7], 0, s[24:25]
	v_readlane_b32 s22, v62, 45
	global_load_dword v55, v[4:5], off
	v_lshl_add_u64 v[4:5], v[4:5], 0, s[24:25]
	s_waitcnt vmcnt(62)
	global_store_dword v[6:7], v23, off
	v_fmac_f32_e32 v24, s3, v23
	v_lshl_add_u64 v[6:7], v[6:7], 0, s[24:25]
	v_readlane_b32 s26, v62, 46
	global_load_dword v56, v[4:5], off
	v_lshl_add_u64 v[4:5], v[4:5], 0, s[24:25]
	s_waitcnt vmcnt(62)
	global_store_dword v[6:7], v24, off
	v_fmac_f32_e32 v25, s22, v24
	v_lshl_add_u64 v[6:7], v[6:7], 0, s[24:25]
	v_readlane_b32 s32, v62, 47
	global_load_dword v57, v[4:5], off
	v_lshl_add_u64 v[4:5], v[4:5], 0, s[24:25]
	s_waitcnt vmcnt(62)
	global_store_dword v[6:7], v25, off
	v_fmac_f32_e32 v26, s26, v25
	v_lshl_add_u64 v[6:7], v[6:7], 0, s[24:25]
	v_readlane_b32 s3, v62, 48
	global_load_dword v58, v[4:5], off
	v_lshl_add_u64 v[4:5], v[4:5], 0, s[24:25]
	s_waitcnt vmcnt(62)
	global_store_dword v[6:7], v26, off
	v_fmac_f32_e32 v27, s32, v26
	v_lshl_add_u64 v[6:7], v[6:7], 0, s[24:25]
	v_readlane_b32 s22, v62, 49
	global_load_dword v59, v[4:5], off
	v_lshl_add_u64 v[4:5], v[4:5], 0, s[24:25]
	s_waitcnt vmcnt(62)
	global_store_dword v[6:7], v27, off
	v_fmac_f32_e32 v28, s3, v27
	v_lshl_add_u64 v[6:7], v[6:7], 0, s[24:25]
	v_readlane_b32 s26, v62, 50
	global_load_dword v20, v[4:5], off
	v_lshl_add_u64 v[4:5], v[4:5], 0, s[24:25]
	s_waitcnt vmcnt(62)
	global_store_dword v[6:7], v28, off
	v_fmac_f32_e32 v29, s22, v28
	v_lshl_add_u64 v[6:7], v[6:7], 0, s[24:25]
	v_readlane_b32 s32, v62, 51
	global_load_dword v21, v[4:5], off
	v_lshl_add_u64 v[4:5], v[4:5], 0, s[24:25]
	s_waitcnt vmcnt(62)
	global_store_dword v[6:7], v29, off
	v_fmac_f32_e32 v30, s26, v29
	v_lshl_add_u64 v[6:7], v[6:7], 0, s[24:25]
	v_readlane_b32 s3, v62, 52
	global_load_dword v22, v[4:5], off
	v_lshl_add_u64 v[4:5], v[4:5], 0, s[24:25]
	s_waitcnt vmcnt(62)
	global_store_dword v[6:7], v30, off
	v_fmac_f32_e32 v31, s32, v30
	v_lshl_add_u64 v[6:7], v[6:7], 0, s[24:25]
	v_readlane_b32 s22, v62, 53
	global_load_dword v23, v[4:5], off
	v_lshl_add_u64 v[4:5], v[4:5], 0, s[24:25]
	s_waitcnt vmcnt(62)
	global_store_dword v[6:7], v31, off
	v_fmac_f32_e32 v32, s3, v31
	v_lshl_add_u64 v[6:7], v[6:7], 0, s[24:25]
	v_readlane_b32 s26, v62, 54
	global_load_dword v24, v[4:5], off
	v_lshl_add_u64 v[4:5], v[4:5], 0, s[24:25]
	s_waitcnt vmcnt(62)
	global_store_dword v[6:7], v32, off
	v_fmac_f32_e32 v33, s22, v32
	v_lshl_add_u64 v[6:7], v[6:7], 0, s[24:25]
	v_readlane_b32 s32, v62, 55
	global_load_dword v25, v[4:5], off
	v_lshl_add_u64 v[4:5], v[4:5], 0, s[24:25]
	s_waitcnt vmcnt(62)
	global_store_dword v[6:7], v33, off
	v_fmac_f32_e32 v34, s26, v33
	v_lshl_add_u64 v[6:7], v[6:7], 0, s[24:25]
	v_readlane_b32 s3, v62, 56
	global_load_dword v26, v[4:5], off
	v_lshl_add_u64 v[4:5], v[4:5], 0, s[24:25]
	s_waitcnt vmcnt(62)
; DI void scan_item(const Params& p, int it) {
;     ...
;   for (int n0 = 0; n0 < NCHUNK; n0 += 26) {
;     float l[26], dd[26];
; #pragma unroll
;     for (int j = 0; j < 26; ++j) { l[j] = L[(size_t)(n0 + j) * 4096]; dd[j] = dc[(n0 + j) * 64]; }
; #pragma unroll
;     for (int j = 0; j < 26; ++j) { L[(size_t)(n0 + j) * 4096] = S; S = dd[j] * S + l[j]; }
;   }
	global_store_dword v[6:7], v34, off
	v_fmac_f32_e32 v35, s32, v34
	v_lshl_add_u64 v[6:7], v[6:7], 0, s[24:25]
	v_readlane_b32 s22, v62, 57
	global_load_dword v27, v[4:5], off
	v_lshl_add_u64 v[4:5], v[4:5], 0, s[24:25]
	s_waitcnt vmcnt(62)
	global_store_dword v[6:7], v35, off
	v_fmac_f32_e32 v36, s3, v35
	v_lshl_add_u64 v[6:7], v[6:7], 0, s[24:25]
	v_readlane_b32 s26, v62, 58
	global_load_dword v28, v[4:5], off
	v_lshl_add_u64 v[4:5], v[4:5], 0, s[24:25]
	s_waitcnt vmcnt(62)
	global_store_dword v[6:7], v36, off
	v_fmac_f32_e32 v37, s22, v36
	v_lshl_add_u64 v[6:7], v[6:7], 0, s[24:25]
	v_readlane_b32 s32, v62, 59
	global_load_dword v29, v[4:5], off
	v_lshl_add_u64 v[4:5], v[4:5], 0, s[24:25]
	s_waitcnt vmcnt(62)
	global_store_dword v[6:7], v37, off
	v_fmac_f32_e32 v38, s26, v37
	v_lshl_add_u64 v[6:7], v[6:7], 0, s[24:25]
	v_readlane_b32 s3, v62, 60
	global_load_dword v30, v[4:5], off
	v_lshl_add_u64 v[4:5], v[4:5], 0, s[24:25]
	s_waitcnt vmcnt(62)
	global_store_dword v[6:7], v38, off
	v_fmac_f32_e32 v39, s32, v38
	v_lshl_add_u64 v[6:7], v[6:7], 0, s[24:25]
	v_readlane_b32 s22, v62, 61
	global_load_dword v31, v[4:5], off
	v_lshl_add_u64 v[4:5], v[4:5], 0, s[24:25]
	s_waitcnt vmcnt(62)
	global_store_dword v[6:7], v39, off
	v_fmac_f32_e32 v40, s3, v39
	v_lshl_add_u64 v[6:7], v[6:7], 0, s[24:25]
	v_readlane_b32 s26, v62, 62
	global_load_dword v32, v[4:5], off
	v_lshl_add_u64 v[4:5], v[4:5], 0, s[24:25]
	s_waitcnt vmcnt(62)
	global_store_dword v[6:7], v40, off
	v_fmac_f32_e32 v41, s22, v40
	v_lshl_add_u64 v[6:7], v[6:7], 0, s[24:25]
	v_readlane_b32 s32, v62, 63
	global_load_dword v33, v[4:5], off
	v_lshl_add_u64 v[4:5], v[4:5], 0, s[24:25]
	s_waitcnt vmcnt(62)
	global_store_dword v[6:7], v41, off
	v_fmac_f32_e32 v42, s26, v41
	v_lshl_add_u64 v[6:7], v[6:7], 0, s[24:25]
	v_readlane_b32 s3, v63, 0
	global_load_dword v34, v[4:5], off
	v_lshl_add_u64 v[4:5], v[4:5], 0, s[24:25]
	s_waitcnt vmcnt(62)
	global_store_dword v[6:7], v42, off
	v_fmac_f32_e32 v43, s32, v42
	v_lshl_add_u64 v[6:7], v[6:7], 0, s[24:25]
	v_readlane_b32 s22, v63, 1
	global_load_dword v35, v[4:5], off
	v_lshl_add_u64 v[4:5], v[4:5], 0, s[24:25]
	s_waitcnt vmcnt(62)
	global_store_dword v[6:7], v43, off
	v_fmac_f32_e32 v44, s3, v43
	v_lshl_add_u64 v[6:7], v[6:7], 0, s[24:25]
	v_readlane_b32 s26, v63, 2
	global_load_dword v36, v[4:5], off
	v_lshl_add_u64 v[4:5], v[4:5], 0, s[24:25]
	s_waitcnt vmcnt(62)
	global_store_dword v[6:7], v44, off
	v_fmac_f32_e32 v45, s22, v44
	v_lshl_add_u64 v[6:7], v[6:7], 0, s[24:25]
	v_readlane_b32 s32, v63, 3
	global_load_dword v37, v[4:5], off
	v_lshl_add_u64 v[4:5], v[4:5], 0, s[24:25]
	s_waitcnt vmcnt(62)
	global_store_dword v[6:7], v45, off
	v_fmac_f32_e32 v46, s26, v45
	v_lshl_add_u64 v[6:7], v[6:7], 0, s[24:25]
	v_readlane_b32 s3, v63, 4
	global_load_dword v38, v[4:5], off
	v_lshl_add_u64 v[4:5], v[4:5], 0, s[24:25]
	s_waitcnt vmcnt(62)
	global_store_dword v[6:7], v46, off
	v_fmac_f32_e32 v47, s32, v46
	v_lshl_add_u64 v[6:7], v[6:7], 0, s[24:25]
	v_readlane_b32 s22, v63, 5
	global_load_dword v39, v[4:5], off
	v_lshl_add_u64 v[4:5], v[4:5], 0, s[24:25]
	s_waitcnt vmcnt(62)
	global_store_dword v[6:7], v47, off
	v_fmac_f32_e32 v48, s3, v47
	v_lshl_add_u64 v[6:7], v[6:7], 0, s[24:25]
	v_readlane_b32 s26, v63, 6
	global_load_dword v40, v[4:5], off
	v_lshl_add_u64 v[4:5], v[4:5], 0, s[24:25]
	s_waitcnt vmcnt(62)
	global_store_dword v[6:7], v48, off
	v_fmac_f32_e32 v49, s22, v48
	v_lshl_add_u64 v[6:7], v[6:7], 0, s[24:25]
	v_readlane_b32 s32, v63, 7
	global_load_dword v41, v[4:5], off
	v_lshl_add_u64 v[4:5], v[4:5], 0, s[24:25]
	s_waitcnt vmcnt(62)
	global_store_dword v[6:7], v49, off
	v_fmac_f32_e32 v50, s26, v49
	v_lshl_add_u64 v[6:7], v[6:7], 0, s[24:25]
	v_readlane_b32 s3, v63, 8
	global_load_dword v42, v[4:5], off
	v_lshl_add_u64 v[4:5], v[4:5], 0, s[24:25]
	s_waitcnt vmcnt(62)
	global_store_dword v[6:7], v50, off
	v_fmac_f32_e32 v51, s32, v50
	v_lshl_add_u64 v[6:7], v[6:7], 0, s[24:25]
	v_readlane_b32 s22, v63, 9
	global_load_dword v43, v[4:5], off
	v_lshl_add_u64 v[4:5], v[4:5], 0, s[24:25]
	s_waitcnt vmcnt(62)
	global_store_dword v[6:7], v51, off
	v_fmac_f32_e32 v52, s3, v51
	v_lshl_add_u64 v[6:7], v[6:7], 0, s[24:25]
	v_readlane_b32 s26, v63, 10
	global_load_dword v44, v[4:5], off
	v_lshl_add_u64 v[4:5], v[4:5], 0, s[24:25]
	s_waitcnt vmcnt(62)
	global_store_dword v[6:7], v52, off
	v_fmac_f32_e32 v53, s22, v52
	v_lshl_add_u64 v[6:7], v[6:7], 0, s[24:25]
	v_readlane_b32 s32, v63, 11
	global_load_dword v45, v[4:5], off
	v_lshl_add_u64 v[4:5], v[4:5], 0, s[24:25]
	s_waitcnt vmcnt(62)
	global_store_dword v[6:7], v53, off
	v_fmac_f32_e32 v54, s26, v53
	v_lshl_add_u64 v[6:7], v[6:7], 0, s[24:25]
	v_readlane_b32 s3, v63, 12
	global_load_dword v46, v[4:5], off
	v_lshl_add_u64 v[4:5], v[4:5], 0, s[24:25]
	s_waitcnt vmcnt(62)
	global_store_dword v[6:7], v54, off
	v_fmac_f32_e32 v55, s32, v54
	v_lshl_add_u64 v[6:7], v[6:7], 0, s[24:25]
	v_readlane_b32 s22, v63, 13
	global_load_dword v47, v[4:5], off
	v_lshl_add_u64 v[4:5], v[4:5], 0, s[24:25]
	s_waitcnt vmcnt(62)
	global_store_dword v[6:7], v55, off
	v_fmac_f32_e32 v56, s3, v55
	v_lshl_add_u64 v[6:7], v[6:7], 0, s[24:25]
	v_readlane_b32 s26, v63, 14
	global_load_dword v48, v[4:5], off
	v_lshl_add_u64 v[4:5], v[4:5], 0, s[24:25]
	s_waitcnt vmcnt(62)
	global_store_dword v[6:7], v56, off
	v_fmac_f32_e32 v57, s22, v56
	v_lshl_add_u64 v[6:7], v[6:7], 0, s[24:25]
	v_readlane_b32 s32, v63, 15
	global_load_dword v49, v[4:5], off
	v_lshl_add_u64 v[4:5], v[4:5], 0, s[24:25]
	s_waitcnt vmcnt(62)
; DI void scan_item(const Params& p, int it) {
;     ...
;   for (int n0 = 0; n0 < NCHUNK; n0 += 26) {
;     float l[26], dd[26];
; #pragma unroll
;     for (int j = 0; j < 26; ++j) { l[j] = L[(size_t)(n0 + j) * 4096]; dd[j] = dc[(n0 + j) * 64]; }
; #pragma unroll
;     for (int j = 0; j < 26; ++j) { L[(size_t)(n0 + j) * 4096] = S; S = dd[j] * S + l[j]; }
;   }
	global_store_dword v[6:7], v57, off
	v_fmac_f32_e32 v58, s26, v57
	v_lshl_add_u64 v[6:7], v[6:7], 0, s[24:25]
	v_readlane_b32 s3, v63, 16
	global_load_dword v50, v[4:5], off
	v_lshl_add_u64 v[4:5], v[4:5], 0, s[24:25]
	s_waitcnt vmcnt(62)
	global_store_dword v[6:7], v58, off
	v_fmac_f32_e32 v59, s32, v58
	v_lshl_add_u64 v[6:7], v[6:7], 0, s[24:25]
	v_readlane_b32 s22, v63, 17
	global_load_dword v51, v[4:5], off
	v_lshl_add_u64 v[4:5], v[4:5], 0, s[24:25]
	s_waitcnt vmcnt(62)
	global_store_dword v[6:7], v59, off
	v_fmac_f32_e32 v20, s3, v59
	v_lshl_add_u64 v[6:7], v[6:7], 0, s[24:25]
	v_readlane_b32 s26, v63, 18
	global_load_dword v52, v[4:5], off
	v_lshl_add_u64 v[4:5], v[4:5], 0, s[24:25]
	s_waitcnt vmcnt(62)
	global_store_dword v[6:7], v20, off
	v_fmac_f32_e32 v21, s22, v20
	v_lshl_add_u64 v[6:7], v[6:7], 0, s[24:25]
	v_readlane_b32 s32, v63, 19
	global_load_dword v53, v[4:5], off
	v_lshl_add_u64 v[4:5], v[4:5], 0, s[24:25]
	s_waitcnt vmcnt(62)
	global_store_dword v[6:7], v21, off
	v_fmac_f32_e32 v22, s26, v21
	v_lshl_add_u64 v[6:7], v[6:7], 0, s[24:25]
	v_readlane_b32 s3, v63, 20
	global_load_dword v54, v[4:5], off
	v_lshl_add_u64 v[4:5], v[4:5], 0, s[24:25]
	s_waitcnt vmcnt(62)
	global_store_dword v[6:7], v22, off
	v_fmac_f32_e32 v23, s32, v22
	v_lshl_add_u64 v[6:7], v[6:7], 0, s[24:25]
	v_readlane_b32 s22, v63, 21
	global_load_dword v55, v[4:5], off
	v_lshl_add_u64 v[4:5], v[4:5], 0, s[24:25]
	s_waitcnt vmcnt(62)
	global_store_dword v[6:7], v23, off
	v_fmac_f32_e32 v24, s3, v23
	v_lshl_add_u64 v[6:7], v[6:7], 0, s[24:25]
	v_readlane_b32 s26, v63, 22
	global_load_dword v56, v[4:5], off
	v_lshl_add_u64 v[4:5], v[4:5], 0, s[24:25]
	s_waitcnt vmcnt(62)
	global_store_dword v[6:7], v24, off
	v_fmac_f32_e32 v25, s22, v24
	v_lshl_add_u64 v[6:7], v[6:7], 0, s[24:25]
	v_readlane_b32 s32, v63, 23
	global_load_dword v57, v[4:5], off
	v_lshl_add_u64 v[4:5], v[4:5], 0, s[24:25]
	s_waitcnt vmcnt(62)
	global_store_dword v[6:7], v25, off
	v_fmac_f32_e32 v26, s26, v25
	v_lshl_add_u64 v[6:7], v[6:7], 0, s[24:25]
	v_readlane_b32 s3, v63, 24
	global_load_dword v58, v[4:5], off
	v_lshl_add_u64 v[4:5], v[4:5], 0, s[24:25]
	s_waitcnt vmcnt(62)
	global_store_dword v[6:7], v26, off
	v_fmac_f32_e32 v27, s32, v26
	v_lshl_add_u64 v[6:7], v[6:7], 0, s[24:25]
	v_readlane_b32 s22, v63, 25
	global_load_dword v59, v[4:5], off
	v_lshl_add_u64 v[4:5], v[4:5], 0, s[24:25]
	s_waitcnt vmcnt(62)
	global_store_dword v[6:7], v27, off
	v_fmac_f32_e32 v28, s3, v27
	v_lshl_add_u64 v[6:7], v[6:7], 0, s[24:25]
	v_readlane_b32 s26, v63, 26
	global_load_dword v20, v[4:5], off
	v_lshl_add_u64 v[4:5], v[4:5], 0, s[24:25]
	s_waitcnt vmcnt(62)
	global_store_dword v[6:7], v28, off
	v_fmac_f32_e32 v29, s22, v28
	v_lshl_add_u64 v[6:7], v[6:7], 0, s[24:25]
	v_readlane_b32 s32, v63, 27
	global_load_dword v21, v[4:5], off
	v_lshl_add_u64 v[4:5], v[4:5], 0, s[24:25]
	s_waitcnt vmcnt(62)
	global_store_dword v[6:7], v29, off
	v_fmac_f32_e32 v30, s26, v29
	v_lshl_add_u64 v[6:7], v[6:7], 0, s[24:25]
	v_readlane_b32 s3, v63, 28
	global_load_dword v22, v[4:5], off
	v_lshl_add_u64 v[4:5], v[4:5], 0, s[24:25]
	s_waitcnt vmcnt(62)
	global_store_dword v[6:7], v30, off
	v_fmac_f32_e32 v31, s32, v30
	v_lshl_add_u64 v[6:7], v[6:7], 0, s[24:25]
	v_readlane_b32 s22, v63, 29
	global_load_dword v23, v[4:5], off
	v_lshl_add_u64 v[4:5], v[4:5], 0, s[24:25]
	s_waitcnt vmcnt(62)
	global_store_dword v[6:7], v31, off
	v_fmac_f32_e32 v32, s3, v31
	v_lshl_add_u64 v[6:7], v[6:7], 0, s[24:25]
	v_readlane_b32 s26, v63, 30
	global_load_dword v24, v[4:5], off
	v_lshl_add_u64 v[4:5], v[4:5], 0, s[24:25]
	s_waitcnt vmcnt(62)
	global_store_dword v[6:7], v32, off
	v_fmac_f32_e32 v33, s22, v32
	v_lshl_add_u64 v[6:7], v[6:7], 0, s[24:25]
	v_readlane_b32 s32, v63, 31
	global_load_dword v25, v[4:5], off
	v_lshl_add_u64 v[4:5], v[4:5], 0, s[24:25]
	s_waitcnt vmcnt(62)
	global_store_dword v[6:7], v33, off
	v_fmac_f32_e32 v34, s26, v33
	v_lshl_add_u64 v[6:7], v[6:7], 0, s[24:25]
	v_readlane_b32 s3, v63, 32
	global_load_dword v26, v[4:5], off
	v_lshl_add_u64 v[4:5], v[4:5], 0, s[24:25]
	s_waitcnt vmcnt(62)
	global_store_dword v[6:7], v34, off
	v_fmac_f32_e32 v35, s32, v34
	v_lshl_add_u64 v[6:7], v[6:7], 0, s[24:25]
	v_readlane_b32 s22, v63, 33
	global_load_dword v27, v[4:5], off
	v_lshl_add_u64 v[4:5], v[4:5], 0, s[24:25]
	s_waitcnt vmcnt(62)
	global_store_dword v[6:7], v35, off
	v_fmac_f32_e32 v36, s3, v35
	v_lshl_add_u64 v[6:7], v[6:7], 0, s[24:25]
	v_readlane_b32 s26, v63, 34
	global_load_dword v28, v[4:5], off
	v_lshl_add_u64 v[4:5], v[4:5], 0, s[24:25]
	s_waitcnt vmcnt(62)
	global_store_dword v[6:7], v36, off
	v_fmac_f32_e32 v37, s22, v36
	v_lshl_add_u64 v[6:7], v[6:7], 0, s[24:25]
	v_readlane_b32 s32, v63, 35
	global_load_dword v29, v[4:5], off
	v_lshl_add_u64 v[4:5], v[4:5], 0, s[24:25]
	s_waitcnt vmcnt(62)
	global_store_dword v[6:7], v37, off
	v_fmac_f32_e32 v38, s26, v37
	v_lshl_add_u64 v[6:7], v[6:7], 0, s[24:25]
	v_readlane_b32 s3, v63, 36
	global_load_dword v30, v[4:5], off
	v_lshl_add_u64 v[4:5], v[4:5], 0, s[24:25]
	s_waitcnt vmcnt(62)
	global_store_dword v[6:7], v38, off
	v_fmac_f32_e32 v39, s32, v38
	v_lshl_add_u64 v[6:7], v[6:7], 0, s[24:25]
	v_readlane_b32 s22, v63, 37
	global_load_dword v31, v[4:5], off
	v_lshl_add_u64 v[4:5], v[4:5], 0, s[24:25]
	s_waitcnt vmcnt(62)
	global_store_dword v[6:7], v39, off
	v_fmac_f32_e32 v40, s3, v39
	v_lshl_add_u64 v[6:7], v[6:7], 0, s[24:25]
	v_readlane_b32 s26, v63, 38
	global_load_dword v32, v[4:5], off
	v_lshl_add_u64 v[4:5], v[4:5], 0, s[24:25]
	s_waitcnt vmcnt(62)
; DI void scan_item(const Params& p, int it) {
;     ...
;   for (int n0 = 0; n0 < NCHUNK; n0 += 26) {
;     float l[26], dd[26];
; #pragma unroll
;     for (int j = 0; j < 26; ++j) { l[j] = L[(size_t)(n0 + j) * 4096]; dd[j] = dc[(n0 + j) * 64]; }
; #pragma unroll
;     for (int j = 0; j < 26; ++j) { L[(size_t)(n0 + j) * 4096] = S; S = dd[j] * S + l[j]; }
;   }
	global_store_dword v[6:7], v40, off
	v_fmac_f32_e32 v41, s22, v40
	v_lshl_add_u64 v[6:7], v[6:7], 0, s[24:25]
	v_readlane_b32 s32, v63, 39
	global_load_dword v33, v[4:5], off
	v_lshl_add_u64 v[4:5], v[4:5], 0, s[24:25]
	s_waitcnt vmcnt(62)
	global_store_dword v[6:7], v41, off
	v_fmac_f32_e32 v42, s26, v41
	v_lshl_add_u64 v[6:7], v[6:7], 0, s[24:25]
	v_readlane_b32 s3, v63, 40
	global_load_dword v34, v[4:5], off
	v_lshl_add_u64 v[4:5], v[4:5], 0, s[24:25]
	s_waitcnt vmcnt(62)
	global_store_dword v[6:7], v42, off
	v_fmac_f32_e32 v43, s32, v42
	v_lshl_add_u64 v[6:7], v[6:7], 0, s[24:25]
	v_readlane_b32 s22, v63, 41
	global_load_dword v35, v[4:5], off
	v_lshl_add_u64 v[4:5], v[4:5], 0, s[24:25]
	s_waitcnt vmcnt(62)
	global_store_dword v[6:7], v43, off
	v_fmac_f32_e32 v44, s3, v43
	v_lshl_add_u64 v[6:7], v[6:7], 0, s[24:25]
	v_readlane_b32 s26, v63, 42
	global_load_dword v36, v[4:5], off
	v_lshl_add_u64 v[4:5], v[4:5], 0, s[24:25]
	s_waitcnt vmcnt(62)
	global_store_dword v[6:7], v44, off
	v_fmac_f32_e32 v45, s22, v44
	v_lshl_add_u64 v[6:7], v[6:7], 0, s[24:25]
	v_readlane_b32 s32, v63, 43
	global_load_dword v37, v[4:5], off
	v_lshl_add_u64 v[4:5], v[4:5], 0, s[24:25]
	s_waitcnt vmcnt(62)
	global_store_dword v[6:7], v45, off
	v_fmac_f32_e32 v46, s26, v45
	v_lshl_add_u64 v[6:7], v[6:7], 0, s[24:25]
	v_readlane_b32 s3, v63, 44
	global_load_dword v38, v[4:5], off
	v_lshl_add_u64 v[4:5], v[4:5], 0, s[24:25]
	s_waitcnt vmcnt(62)
	global_store_dword v[6:7], v46, off
	v_fmac_f32_e32 v47, s32, v46
	v_lshl_add_u64 v[6:7], v[6:7], 0, s[24:25]
	v_readlane_b32 s22, v63, 45
	global_load_dword v39, v[4:5], off
	v_lshl_add_u64 v[4:5], v[4:5], 0, s[24:25]
	s_waitcnt vmcnt(62)
	global_store_dword v[6:7], v47, off
	v_fmac_f32_e32 v48, s3, v47
	v_lshl_add_u64 v[6:7], v[6:7], 0, s[24:25]
	v_readlane_b32 s26, v63, 46
	global_load_dword v40, v[4:5], off
	v_lshl_add_u64 v[4:5], v[4:5], 0, s[24:25]
	s_waitcnt vmcnt(62)
	global_store_dword v[6:7], v48, off
	v_fmac_f32_e32 v49, s22, v48
	v_lshl_add_u64 v[6:7], v[6:7], 0, s[24:25]
	v_readlane_b32 s32, v63, 47
	global_load_dword v41, v[4:5], off
	v_lshl_add_u64 v[4:5], v[4:5], 0, s[24:25]
	s_waitcnt vmcnt(62)
	global_store_dword v[6:7], v49, off
	v_fmac_f32_e32 v50, s26, v49
	v_lshl_add_u64 v[6:7], v[6:7], 0, s[24:25]
	v_readlane_b32 s3, v63, 48
	global_load_dword v42, v[4:5], off
	v_lshl_add_u64 v[4:5], v[4:5], 0, s[24:25]
	s_waitcnt vmcnt(62)
	global_store_dword v[6:7], v50, off
	v_fmac_f32_e32 v51, s32, v50
	v_lshl_add_u64 v[6:7], v[6:7], 0, s[24:25]
	v_readlane_b32 s22, v63, 49
	global_load_dword v43, v[4:5], off
	v_lshl_add_u64 v[4:5], v[4:5], 0, s[24:25]
	s_waitcnt vmcnt(62)
	global_store_dword v[6:7], v51, off
	v_fmac_f32_e32 v52, s3, v51
	v_lshl_add_u64 v[6:7], v[6:7], 0, s[24:25]
	v_readlane_b32 s26, v63, 50
	global_load_dword v44, v[4:5], off
	v_lshl_add_u64 v[4:5], v[4:5], 0, s[24:25]
	s_waitcnt vmcnt(62)
	global_store_dword v[6:7], v52, off
	v_fmac_f32_e32 v53, s22, v52
	v_lshl_add_u64 v[6:7], v[6:7], 0, s[24:25]
	v_readlane_b32 s32, v63, 51
	global_load_dword v45, v[4:5], off
	v_lshl_add_u64 v[4:5], v[4:5], 0, s[24:25]
	s_waitcnt vmcnt(62)
	global_store_dword v[6:7], v53, off
	v_fmac_f32_e32 v54, s26, v53
	v_lshl_add_u64 v[6:7], v[6:7], 0, s[24:25]
	v_readlane_b32 s3, v63, 52
	global_load_dword v46, v[4:5], off
	v_lshl_add_u64 v[4:5], v[4:5], 0, s[24:25]
	s_waitcnt vmcnt(62)
	global_store_dword v[6:7], v54, off
	v_fmac_f32_e32 v55, s32, v54
	v_lshl_add_u64 v[6:7], v[6:7], 0, s[24:25]
	v_readlane_b32 s22, v63, 53
	global_load_dword v47, v[4:5], off
	v_lshl_add_u64 v[4:5], v[4:5], 0, s[24:25]
	s_waitcnt vmcnt(62)
	global_store_dword v[6:7], v55, off
	v_fmac_f32_e32 v56, s3, v55
	v_lshl_add_u64 v[6:7], v[6:7], 0, s[24:25]
	v_readlane_b32 s26, v63, 54
	global_load_dword v48, v[4:5], off
	v_lshl_add_u64 v[4:5], v[4:5], 0, s[24:25]
	s_waitcnt vmcnt(62)
	global_store_dword v[6:7], v56, off
	v_fmac_f32_e32 v57, s22, v56
	v_lshl_add_u64 v[6:7], v[6:7], 0, s[24:25]
	v_readlane_b32 s32, v63, 55
	global_load_dword v49, v[4:5], off
	v_lshl_add_u64 v[4:5], v[4:5], 0, s[24:25]
	s_waitcnt vmcnt(62)
	global_store_dword v[6:7], v57, off
	v_fmac_f32_e32 v58, s26, v57
	v_lshl_add_u64 v[6:7], v[6:7], 0, s[24:25]
	v_readlane_b32 s3, v63, 56
	global_load_dword v50, v[4:5], off
	v_lshl_add_u64 v[4:5], v[4:5], 0, s[24:25]
	s_waitcnt vmcnt(62)
	global_store_dword v[6:7], v58, off
	v_fmac_f32_e32 v59, s32, v58
	v_lshl_add_u64 v[6:7], v[6:7], 0, s[24:25]
	v_readlane_b32 s22, v63, 57
	global_load_dword v51, v[4:5], off
	v_lshl_add_u64 v[4:5], v[4:5], 0, s[24:25]
	s_waitcnt vmcnt(62)
	global_store_dword v[6:7], v59, off
	v_fmac_f32_e32 v20, s3, v59
	v_lshl_add_u64 v[6:7], v[6:7], 0, s[24:25]
	v_readlane_b32 s26, v63, 58
	global_load_dword v52, v[4:5], off
	v_lshl_add_u64 v[4:5], v[4:5], 0, s[24:25]
	s_waitcnt vmcnt(62)
	global_store_dword v[6:7], v20, off
	v_fmac_f32_e32 v21, s22, v20
	v_lshl_add_u64 v[6:7], v[6:7], 0, s[24:25]
	v_readlane_b32 s32, v63, 59
	global_load_dword v53, v[4:5], off
	v_lshl_add_u64 v[4:5], v[4:5], 0, s[24:25]
	s_waitcnt vmcnt(62)
	global_store_dword v[6:7], v21, off
	v_fmac_f32_e32 v22, s26, v21
	v_lshl_add_u64 v[6:7], v[6:7], 0, s[24:25]
	v_readlane_b32 s3, v63, 60
	global_load_dword v54, v[4:5], off
	v_lshl_add_u64 v[4:5], v[4:5], 0, s[24:25]
	s_waitcnt vmcnt(62)
	global_store_dword v[6:7], v22, off
	v_fmac_f32_e32 v23, s32, v22
	v_lshl_add_u64 v[6:7], v[6:7], 0, s[24:25]
	v_readlane_b32 s22, v63, 61
	global_load_dword v55, v[4:5], off
	v_lshl_add_u64 v[4:5], v[4:5], 0, s[24:25]
	s_waitcnt vmcnt(62)
; DI void scan_item(const Params& p, int it) {
;     ...
;   for (int n0 = 0; n0 < NCHUNK; n0 += 26) {
;     float l[26], dd[26];
; #pragma unroll
;     for (int j = 0; j < 26; ++j) { l[j] = L[(size_t)(n0 + j) * 4096]; dd[j] = dc[(n0 + j) * 64]; }
; #pragma unroll
;     for (int j = 0; j < 26; ++j) { L[(size_t)(n0 + j) * 4096] = S; S = dd[j] * S + l[j]; }
;   }
	global_store_dword v[6:7], v23, off
	v_fmac_f32_e32 v24, s3, v23
	v_lshl_add_u64 v[6:7], v[6:7], 0, s[24:25]
	v_readlane_b32 s26, v63, 62
	global_load_dword v56, v[4:5], off
	v_lshl_add_u64 v[4:5], v[4:5], 0, s[24:25]
	s_waitcnt vmcnt(62)
	global_store_dword v[6:7], v24, off
	v_fmac_f32_e32 v25, s22, v24
	v_lshl_add_u64 v[6:7], v[6:7], 0, s[24:25]
	v_readlane_b32 s32, v63, 63
	global_load_dword v57, v[4:5], off
	v_lshl_add_u64 v[4:5], v[4:5], 0, s[24:25]
	s_waitcnt vmcnt(62)
	global_store_dword v[6:7], v25, off
	v_fmac_f32_e32 v26, s26, v25
	v_lshl_add_u64 v[6:7], v[6:7], 0, s[24:25]
	v_readlane_b32 s3, v64, 0
	global_load_dword v58, v[4:5], off
	v_lshl_add_u64 v[4:5], v[4:5], 0, s[24:25]
	s_waitcnt vmcnt(62)
	global_store_dword v[6:7], v26, off
	v_fmac_f32_e32 v27, s32, v26
	v_lshl_add_u64 v[6:7], v[6:7], 0, s[24:25]
	v_readlane_b32 s22, v64, 1
	global_load_dword v59, v[4:5], off
	v_lshl_add_u64 v[4:5], v[4:5], 0, s[24:25]
	s_waitcnt vmcnt(62)
	global_store_dword v[6:7], v27, off
	v_fmac_f32_e32 v28, s3, v27
	v_lshl_add_u64 v[6:7], v[6:7], 0, s[24:25]
	v_readlane_b32 s26, v64, 2
	global_load_dword v20, v[4:5], off
	v_lshl_add_u64 v[4:5], v[4:5], 0, s[24:25]
	s_waitcnt vmcnt(62)
	global_store_dword v[6:7], v28, off
	v_fmac_f32_e32 v29, s22, v28
	v_lshl_add_u64 v[6:7], v[6:7], 0, s[24:25]
	v_readlane_b32 s32, v64, 3
	global_load_dword v21, v[4:5], off
	v_lshl_add_u64 v[4:5], v[4:5], 0, s[24:25]
	s_waitcnt vmcnt(62)
	global_store_dword v[6:7], v29, off
	v_fmac_f32_e32 v30, s26, v29
	v_lshl_add_u64 v[6:7], v[6:7], 0, s[24:25]
	v_readlane_b32 s3, v64, 4
	global_load_dword v22, v[4:5], off
	v_lshl_add_u64 v[4:5], v[4:5], 0, s[24:25]
	s_waitcnt vmcnt(62)
	global_store_dword v[6:7], v30, off
	v_fmac_f32_e32 v31, s32, v30
	v_lshl_add_u64 v[6:7], v[6:7], 0, s[24:25]
	v_readlane_b32 s22, v64, 5
	global_load_dword v23, v[4:5], off
	v_lshl_add_u64 v[4:5], v[4:5], 0, s[24:25]
	s_waitcnt vmcnt(62)
	global_store_dword v[6:7], v31, off
	v_fmac_f32_e32 v32, s3, v31
	v_lshl_add_u64 v[6:7], v[6:7], 0, s[24:25]
	v_readlane_b32 s26, v64, 6
	global_load_dword v24, v[4:5], off
	v_lshl_add_u64 v[4:5], v[4:5], 0, s[24:25]
	s_waitcnt vmcnt(62)
	global_store_dword v[6:7], v32, off
	v_fmac_f32_e32 v33, s22, v32
	v_lshl_add_u64 v[6:7], v[6:7], 0, s[24:25]
	v_readlane_b32 s32, v64, 7
	global_load_dword v25, v[4:5], off
	v_lshl_add_u64 v[4:5], v[4:5], 0, s[24:25]
	s_waitcnt vmcnt(62)
	global_store_dword v[6:7], v33, off
	v_fmac_f32_e32 v34, s26, v33
	v_lshl_add_u64 v[6:7], v[6:7], 0, s[24:25]
	v_readlane_b32 s3, v64, 8
	global_load_dword v26, v[4:5], off
	v_lshl_add_u64 v[4:5], v[4:5], 0, s[24:25]
	s_waitcnt vmcnt(62)
	global_store_dword v[6:7], v34, off
	v_fmac_f32_e32 v35, s32, v34
	v_lshl_add_u64 v[6:7], v[6:7], 0, s[24:25]
	v_readlane_b32 s22, v64, 9
	global_load_dword v27, v[4:5], off
	v_lshl_add_u64 v[4:5], v[4:5], 0, s[24:25]
	s_waitcnt vmcnt(62)
	global_store_dword v[6:7], v35, off
	v_fmac_f32_e32 v36, s3, v35
	v_lshl_add_u64 v[6:7], v[6:7], 0, s[24:25]
	v_readlane_b32 s26, v64, 10
	global_load_dword v28, v[4:5], off
	v_lshl_add_u64 v[4:5], v[4:5], 0, s[24:25]
	s_waitcnt vmcnt(62)
	global_store_dword v[6:7], v36, off
	v_fmac_f32_e32 v37, s22, v36
	v_lshl_add_u64 v[6:7], v[6:7], 0, s[24:25]
	v_readlane_b32 s32, v64, 11
	global_load_dword v29, v[4:5], off
	v_lshl_add_u64 v[4:5], v[4:5], 0, s[24:25]
	s_waitcnt vmcnt(62)
	global_store_dword v[6:7], v37, off
	v_fmac_f32_e32 v38, s26, v37
	v_lshl_add_u64 v[6:7], v[6:7], 0, s[24:25]
	v_readlane_b32 s3, v64, 12
	global_load_dword v30, v[4:5], off
	v_lshl_add_u64 v[4:5], v[4:5], 0, s[24:25]
	s_waitcnt vmcnt(62)
	global_store_dword v[6:7], v38, off
	v_fmac_f32_e32 v39, s32, v38
	v_lshl_add_u64 v[6:7], v[6:7], 0, s[24:25]
	v_readlane_b32 s22, v64, 13
	global_load_dword v31, v[4:5], off
	v_lshl_add_u64 v[4:5], v[4:5], 0, s[24:25]
	s_waitcnt vmcnt(62)
	global_store_dword v[6:7], v39, off
	v_fmac_f32_e32 v40, s3, v39
	v_lshl_add_u64 v[6:7], v[6:7], 0, s[24:25]
	v_readlane_b32 s26, v64, 14
	global_load_dword v32, v[4:5], off
	v_lshl_add_u64 v[4:5], v[4:5], 0, s[24:25]
	s_waitcnt vmcnt(62)
	global_store_dword v[6:7], v40, off
	v_fmac_f32_e32 v41, s22, v40
	v_lshl_add_u64 v[6:7], v[6:7], 0, s[24:25]
	v_readlane_b32 s32, v64, 15
	global_load_dword v33, v[4:5], off
	v_lshl_add_u64 v[4:5], v[4:5], 0, s[24:25]
	s_waitcnt vmcnt(62)
	global_store_dword v[6:7], v41, off
	v_fmac_f32_e32 v42, s26, v41
	v_lshl_add_u64 v[6:7], v[6:7], 0, s[24:25]
	v_readlane_b32 s3, v64, 16
	global_load_dword v34, v[4:5], off
	v_lshl_add_u64 v[4:5], v[4:5], 0, s[24:25]
	s_waitcnt vmcnt(62)
	global_store_dword v[6:7], v42, off
	v_fmac_f32_e32 v43, s32, v42
	v_lshl_add_u64 v[6:7], v[6:7], 0, s[24:25]
	v_readlane_b32 s22, v64, 17
	global_load_dword v35, v[4:5], off
	v_lshl_add_u64 v[4:5], v[4:5], 0, s[24:25]
	s_waitcnt vmcnt(62)
	global_store_dword v[6:7], v43, off
	v_fmac_f32_e32 v44, s3, v43
	v_lshl_add_u64 v[6:7], v[6:7], 0, s[24:25]
	v_readlane_b32 s26, v64, 18
	global_load_dword v36, v[4:5], off
	v_lshl_add_u64 v[4:5], v[4:5], 0, s[24:25]
	s_waitcnt vmcnt(62)
	global_store_dword v[6:7], v44, off
	v_fmac_f32_e32 v45, s22, v44
	v_lshl_add_u64 v[6:7], v[6:7], 0, s[24:25]
	v_readlane_b32 s32, v64, 19
	global_load_dword v37, v[4:5], off
	v_lshl_add_u64 v[4:5], v[4:5], 0, s[24:25]
	s_waitcnt vmcnt(62)
	global_store_dword v[6:7], v45, off
	v_fmac_f32_e32 v46, s26, v45
	v_lshl_add_u64 v[6:7], v[6:7], 0, s[24:25]
	v_readlane_b32 s3, v64, 20
	global_load_dword v38, v[4:5], off
	v_lshl_add_u64 v[4:5], v[4:5], 0, s[24:25]
	s_waitcnt vmcnt(62)
; DI void scan_item(const Params& p, int it) {
;     ...
;   for (int n0 = 0; n0 < NCHUNK; n0 += 26) {
;     float l[26], dd[26];
; #pragma unroll
;     for (int j = 0; j < 26; ++j) { l[j] = L[(size_t)(n0 + j) * 4096]; dd[j] = dc[(n0 + j) * 64]; }
; #pragma unroll
;     for (int j = 0; j < 26; ++j) { L[(size_t)(n0 + j) * 4096] = S; S = dd[j] * S + l[j]; }
;   }
	global_store_dword v[6:7], v46, off
	v_fmac_f32_e32 v47, s32, v46
	v_lshl_add_u64 v[6:7], v[6:7], 0, s[24:25]
	v_readlane_b32 s22, v64, 21
	global_load_dword v39, v[4:5], off
	v_lshl_add_u64 v[4:5], v[4:5], 0, s[24:25]
	s_waitcnt vmcnt(62)
	global_store_dword v[6:7], v47, off
	v_fmac_f32_e32 v48, s3, v47
	v_lshl_add_u64 v[6:7], v[6:7], 0, s[24:25]
	v_readlane_b32 s26, v64, 22
	global_load_dword v40, v[4:5], off
	v_lshl_add_u64 v[4:5], v[4:5], 0, s[24:25]
	s_waitcnt vmcnt(62)
	global_store_dword v[6:7], v48, off
	v_fmac_f32_e32 v49, s22, v48
	v_lshl_add_u64 v[6:7], v[6:7], 0, s[24:25]
	v_readlane_b32 s32, v64, 23
	global_load_dword v41, v[4:5], off
	v_lshl_add_u64 v[4:5], v[4:5], 0, s[24:25]
	s_waitcnt vmcnt(62)
	global_store_dword v[6:7], v49, off
	v_fmac_f32_e32 v50, s26, v49
	v_lshl_add_u64 v[6:7], v[6:7], 0, s[24:25]
	v_readlane_b32 s3, v64, 24
	global_load_dword v42, v[4:5], off
	v_lshl_add_u64 v[4:5], v[4:5], 0, s[24:25]
	s_waitcnt vmcnt(62)
	global_store_dword v[6:7], v50, off
	v_fmac_f32_e32 v51, s32, v50
	v_lshl_add_u64 v[6:7], v[6:7], 0, s[24:25]
	v_readlane_b32 s22, v64, 25
	global_load_dword v43, v[4:5], off
	v_lshl_add_u64 v[4:5], v[4:5], 0, s[24:25]
	s_waitcnt vmcnt(62)
	global_store_dword v[6:7], v51, off
	v_fmac_f32_e32 v52, s3, v51
	v_lshl_add_u64 v[6:7], v[6:7], 0, s[24:25]
	v_readlane_b32 s26, v64, 26
	global_load_dword v44, v[4:5], off
	v_lshl_add_u64 v[4:5], v[4:5], 0, s[24:25]
	s_waitcnt vmcnt(62)
	global_store_dword v[6:7], v52, off
	v_fmac_f32_e32 v53, s22, v52
	v_lshl_add_u64 v[6:7], v[6:7], 0, s[24:25]
	v_readlane_b32 s32, v64, 27
	global_load_dword v45, v[4:5], off
	v_lshl_add_u64 v[4:5], v[4:5], 0, s[24:25]
	s_waitcnt vmcnt(62)
	global_store_dword v[6:7], v53, off
	v_fmac_f32_e32 v54, s26, v53
	v_lshl_add_u64 v[6:7], v[6:7], 0, s[24:25]
	v_readlane_b32 s3, v64, 28
	global_load_dword v46, v[4:5], off
	v_lshl_add_u64 v[4:5], v[4:5], 0, s[24:25]
	s_waitcnt vmcnt(62)
	global_store_dword v[6:7], v54, off
	v_fmac_f32_e32 v55, s32, v54
	v_lshl_add_u64 v[6:7], v[6:7], 0, s[24:25]
	v_readlane_b32 s22, v64, 29
	global_load_dword v47, v[4:5], off
	v_lshl_add_u64 v[4:5], v[4:5], 0, s[24:25]
	s_waitcnt vmcnt(62)
	global_store_dword v[6:7], v55, off
	v_fmac_f32_e32 v56, s3, v55
	v_lshl_add_u64 v[6:7], v[6:7], 0, s[24:25]
	v_readlane_b32 s26, v64, 30
	global_load_dword v48, v[4:5], off
	v_lshl_add_u64 v[4:5], v[4:5], 0, s[24:25]
	s_waitcnt vmcnt(62)
	global_store_dword v[6:7], v56, off
	v_fmac_f32_e32 v57, s22, v56
	v_lshl_add_u64 v[6:7], v[6:7], 0, s[24:25]
	v_readlane_b32 s32, v64, 31
	global_load_dword v49, v[4:5], off
	v_lshl_add_u64 v[4:5], v[4:5], 0, s[24:25]
	s_waitcnt vmcnt(62)
	global_store_dword v[6:7], v57, off
	v_fmac_f32_e32 v58, s26, v57
	v_lshl_add_u64 v[6:7], v[6:7], 0, s[24:25]
	v_readlane_b32 s3, v64, 32
	global_load_dword v50, v[4:5], off
	v_lshl_add_u64 v[4:5], v[4:5], 0, s[24:25]
	s_waitcnt vmcnt(62)
	global_store_dword v[6:7], v58, off
	v_fmac_f32_e32 v59, s32, v58
	v_lshl_add_u64 v[6:7], v[6:7], 0, s[24:25]
	v_readlane_b32 s22, v64, 33
	global_load_dword v51, v[4:5], off
	v_lshl_add_u64 v[4:5], v[4:5], 0, s[24:25]
	s_waitcnt vmcnt(62)
	global_store_dword v[6:7], v59, off
	v_fmac_f32_e32 v20, s3, v59
	v_lshl_add_u64 v[6:7], v[6:7], 0, s[24:25]
	v_readlane_b32 s26, v64, 34
	global_load_dword v52, v[4:5], off
	v_lshl_add_u64 v[4:5], v[4:5], 0, s[24:25]
	s_waitcnt vmcnt(62)
	global_store_dword v[6:7], v20, off
	v_fmac_f32_e32 v21, s22, v20
	v_lshl_add_u64 v[6:7], v[6:7], 0, s[24:25]
	v_readlane_b32 s32, v64, 35
	global_load_dword v53, v[4:5], off
	v_lshl_add_u64 v[4:5], v[4:5], 0, s[24:25]
	s_waitcnt vmcnt(62)
	global_store_dword v[6:7], v21, off
	v_fmac_f32_e32 v22, s26, v21
	v_lshl_add_u64 v[6:7], v[6:7], 0, s[24:25]
	v_readlane_b32 s3, v64, 36
	global_load_dword v54, v[4:5], off
	v_lshl_add_u64 v[4:5], v[4:5], 0, s[24:25]
	s_waitcnt vmcnt(62)
	global_store_dword v[6:7], v22, off
	v_fmac_f32_e32 v23, s32, v22
	v_lshl_add_u64 v[6:7], v[6:7], 0, s[24:25]
	v_readlane_b32 s22, v64, 37
	global_load_dword v55, v[4:5], off
	v_lshl_add_u64 v[4:5], v[4:5], 0, s[24:25]
	s_waitcnt vmcnt(62)
	global_store_dword v[6:7], v23, off
	v_fmac_f32_e32 v24, s3, v23
	v_lshl_add_u64 v[6:7], v[6:7], 0, s[24:25]
	v_readlane_b32 s26, v64, 38
	global_load_dword v56, v[4:5], off
	v_lshl_add_u64 v[4:5], v[4:5], 0, s[24:25]
	s_waitcnt vmcnt(62)
	global_store_dword v[6:7], v24, off
	v_fmac_f32_e32 v25, s22, v24
	v_lshl_add_u64 v[6:7], v[6:7], 0, s[24:25]
	v_readlane_b32 s32, v64, 39
	global_load_dword v57, v[4:5], off
	v_lshl_add_u64 v[4:5], v[4:5], 0, s[24:25]
	s_waitcnt vmcnt(62)
	global_store_dword v[6:7], v25, off
	v_fmac_f32_e32 v26, s26, v25
	v_lshl_add_u64 v[6:7], v[6:7], 0, s[24:25]
	v_readlane_b32 s3, v64, 40
	global_load_dword v58, v[4:5], off
	v_lshl_add_u64 v[4:5], v[4:5], 0, s[24:25]
	s_waitcnt vmcnt(62)
	global_store_dword v[6:7], v26, off
	v_fmac_f32_e32 v27, s32, v26
	v_lshl_add_u64 v[6:7], v[6:7], 0, s[24:25]
	v_readlane_b32 s22, v64, 41
	global_load_dword v59, v[4:5], off
	v_lshl_add_u64 v[4:5], v[4:5], 0, s[24:25]
	s_waitcnt vmcnt(62)
	global_store_dword v[6:7], v27, off
	v_fmac_f32_e32 v28, s3, v27
	v_lshl_add_u64 v[6:7], v[6:7], 0, s[24:25]
	v_readlane_b32 s26, v64, 42
	global_load_dword v20, v[4:5], off
	v_lshl_add_u64 v[4:5], v[4:5], 0, s[24:25]
	s_waitcnt vmcnt(62)
	global_store_dword v[6:7], v28, off
	v_fmac_f32_e32 v29, s22, v28
	v_lshl_add_u64 v[6:7], v[6:7], 0, s[24:25]
	v_readlane_b32 s32, v64, 43
	global_load_dword v21, v[4:5], off
	v_lshl_add_u64 v[4:5], v[4:5], 0, s[24:25]
	s_waitcnt vmcnt(62)
; DI void scan_item(const Params& p, int it) {
;     ...
;   for (int n0 = 0; n0 < NCHUNK; n0 += 26) {
;     float l[26], dd[26];
; #pragma unroll
;     for (int j = 0; j < 26; ++j) { l[j] = L[(size_t)(n0 + j) * 4096]; dd[j] = dc[(n0 + j) * 64]; }
; #pragma unroll
;     for (int j = 0; j < 26; ++j) { L[(size_t)(n0 + j) * 4096] = S; S = dd[j] * S + l[j]; }
;   }
	global_store_dword v[6:7], v29, off
	v_fmac_f32_e32 v30, s26, v29
	v_lshl_add_u64 v[6:7], v[6:7], 0, s[24:25]
	v_readlane_b32 s3, v64, 44
	global_load_dword v22, v[4:5], off
	v_lshl_add_u64 v[4:5], v[4:5], 0, s[24:25]
	s_waitcnt vmcnt(62)
	global_store_dword v[6:7], v30, off
	v_fmac_f32_e32 v31, s32, v30
	v_lshl_add_u64 v[6:7], v[6:7], 0, s[24:25]
	v_readlane_b32 s22, v64, 45
	global_load_dword v23, v[4:5], off
	v_lshl_add_u64 v[4:5], v[4:5], 0, s[24:25]
	s_waitcnt vmcnt(62)
	global_store_dword v[6:7], v31, off
	v_fmac_f32_e32 v32, s3, v31
	v_lshl_add_u64 v[6:7], v[6:7], 0, s[24:25]
	v_readlane_b32 s26, v64, 46
	global_load_dword v24, v[4:5], off
	v_lshl_add_u64 v[4:5], v[4:5], 0, s[24:25]
	s_waitcnt vmcnt(62)
	global_store_dword v[6:7], v32, off
	v_fmac_f32_e32 v33, s22, v32
	v_lshl_add_u64 v[6:7], v[6:7], 0, s[24:25]
	v_readlane_b32 s32, v64, 47
	global_load_dword v25, v[4:5], off
	v_lshl_add_u64 v[4:5], v[4:5], 0, s[24:25]
	s_waitcnt vmcnt(62)
	global_store_dword v[6:7], v33, off
	v_fmac_f32_e32 v34, s26, v33
	v_lshl_add_u64 v[6:7], v[6:7], 0, s[24:25]
	v_readlane_b32 s3, v64, 48
	global_load_dword v26, v[4:5], off
	v_lshl_add_u64 v[4:5], v[4:5], 0, s[24:25]
	s_waitcnt vmcnt(62)
	global_store_dword v[6:7], v34, off
	v_fmac_f32_e32 v35, s32, v34
	v_lshl_add_u64 v[6:7], v[6:7], 0, s[24:25]
	v_readlane_b32 s22, v64, 49
	global_load_dword v27, v[4:5], off
	v_lshl_add_u64 v[4:5], v[4:5], 0, s[24:25]
	s_waitcnt vmcnt(62)
	global_store_dword v[6:7], v35, off
	v_fmac_f32_e32 v36, s3, v35
	v_lshl_add_u64 v[6:7], v[6:7], 0, s[24:25]
	v_readlane_b32 s26, v64, 50
	global_load_dword v28, v[4:5], off
	v_lshl_add_u64 v[4:5], v[4:5], 0, s[24:25]
	s_waitcnt vmcnt(62)
	global_store_dword v[6:7], v36, off
	v_fmac_f32_e32 v37, s22, v36
	v_lshl_add_u64 v[6:7], v[6:7], 0, s[24:25]
	v_readlane_b32 s32, v64, 51
	global_load_dword v29, v[4:5], off
	v_lshl_add_u64 v[4:5], v[4:5], 0, s[24:25]
	s_waitcnt vmcnt(62)
	global_store_dword v[6:7], v37, off
	v_fmac_f32_e32 v38, s26, v37
	v_lshl_add_u64 v[6:7], v[6:7], 0, s[24:25]
	v_readlane_b32 s3, v64, 52
	global_load_dword v30, v[4:5], off
	v_lshl_add_u64 v[4:5], v[4:5], 0, s[24:25]
	s_waitcnt vmcnt(62)
	global_store_dword v[6:7], v38, off
	v_fmac_f32_e32 v39, s32, v38
	v_lshl_add_u64 v[6:7], v[6:7], 0, s[24:25]
	v_readlane_b32 s22, v64, 53
	global_load_dword v31, v[4:5], off
	v_lshl_add_u64 v[4:5], v[4:5], 0, s[24:25]
	s_waitcnt vmcnt(62)
	global_store_dword v[6:7], v39, off
	v_fmac_f32_e32 v40, s3, v39
	v_lshl_add_u64 v[6:7], v[6:7], 0, s[24:25]
	v_readlane_b32 s26, v64, 54
	global_load_dword v32, v[4:5], off
	v_lshl_add_u64 v[4:5], v[4:5], 0, s[24:25]
	s_waitcnt vmcnt(62)
	global_store_dword v[6:7], v40, off
	v_fmac_f32_e32 v41, s22, v40
	v_lshl_add_u64 v[6:7], v[6:7], 0, s[24:25]
	v_readlane_b32 s32, v64, 55
	global_load_dword v33, v[4:5], off
	v_lshl_add_u64 v[4:5], v[4:5], 0, s[24:25]
	s_waitcnt vmcnt(62)
	global_store_dword v[6:7], v41, off
	v_fmac_f32_e32 v42, s26, v41
	v_lshl_add_u64 v[6:7], v[6:7], 0, s[24:25]
	v_readlane_b32 s3, v64, 56
	global_load_dword v34, v[4:5], off
	v_lshl_add_u64 v[4:5], v[4:5], 0, s[24:25]
	s_waitcnt vmcnt(62)
	global_store_dword v[6:7], v42, off
	v_fmac_f32_e32 v43, s32, v42
	v_lshl_add_u64 v[6:7], v[6:7], 0, s[24:25]
	v_readlane_b32 s22, v64, 57
	global_load_dword v35, v[4:5], off
	v_lshl_add_u64 v[4:5], v[4:5], 0, s[24:25]
	s_waitcnt vmcnt(62)
	global_store_dword v[6:7], v43, off
	v_fmac_f32_e32 v44, s3, v43
	v_lshl_add_u64 v[6:7], v[6:7], 0, s[24:25]
	v_readlane_b32 s26, v64, 58
	global_load_dword v36, v[4:5], off
	v_lshl_add_u64 v[4:5], v[4:5], 0, s[24:25]
	s_waitcnt vmcnt(62)
	global_store_dword v[6:7], v44, off
	v_fmac_f32_e32 v45, s22, v44
	v_lshl_add_u64 v[6:7], v[6:7], 0, s[24:25]
	v_readlane_b32 s32, v64, 59
	global_load_dword v37, v[4:5], off
	v_lshl_add_u64 v[4:5], v[4:5], 0, s[24:25]
	s_waitcnt vmcnt(62)
	global_store_dword v[6:7], v45, off
	v_fmac_f32_e32 v46, s26, v45
	v_lshl_add_u64 v[6:7], v[6:7], 0, s[24:25]
	v_readlane_b32 s3, v64, 60
	global_load_dword v38, v[4:5], off
	v_lshl_add_u64 v[4:5], v[4:5], 0, s[24:25]
	s_waitcnt vmcnt(62)
	global_store_dword v[6:7], v46, off
	v_fmac_f32_e32 v47, s32, v46
	v_lshl_add_u64 v[6:7], v[6:7], 0, s[24:25]
	v_readlane_b32 s22, v64, 61
	global_load_dword v39, v[4:5], off
	v_lshl_add_u64 v[4:5], v[4:5], 0, s[24:25]
	s_waitcnt vmcnt(62)
	global_store_dword v[6:7], v47, off
	v_fmac_f32_e32 v48, s3, v47
	v_lshl_add_u64 v[6:7], v[6:7], 0, s[24:25]
	v_readlane_b32 s26, v64, 62
	global_load_dword v40, v[4:5], off
	v_lshl_add_u64 v[4:5], v[4:5], 0, s[24:25]
	s_waitcnt vmcnt(62)
	global_store_dword v[6:7], v48, off
	v_fmac_f32_e32 v49, s22, v48
	v_lshl_add_u64 v[6:7], v[6:7], 0, s[24:25]
	v_readlane_b32 s32, v64, 63
	global_load_dword v41, v[4:5], off
	v_lshl_add_u64 v[4:5], v[4:5], 0, s[24:25]
	s_waitcnt vmcnt(62)
	global_store_dword v[6:7], v49, off
	v_fmac_f32_e32 v50, s26, v49
	v_lshl_add_u64 v[6:7], v[6:7], 0, s[24:25]
	v_readlane_b32 s3, v65, 0
	global_load_dword v42, v[4:5], off
	v_lshl_add_u64 v[4:5], v[4:5], 0, s[24:25]
	s_waitcnt vmcnt(62)
	global_store_dword v[6:7], v50, off
	v_fmac_f32_e32 v51, s32, v50
	v_lshl_add_u64 v[6:7], v[6:7], 0, s[24:25]
	v_readlane_b32 s22, v65, 1
	global_load_dword v43, v[4:5], off
	v_lshl_add_u64 v[4:5], v[4:5], 0, s[24:25]
	s_waitcnt vmcnt(62)
	global_store_dword v[6:7], v51, off
	v_fmac_f32_e32 v52, s3, v51
	v_lshl_add_u64 v[6:7], v[6:7], 0, s[24:25]
	v_readlane_b32 s26, v65, 2
	global_load_dword v44, v[4:5], off
	v_lshl_add_u64 v[4:5], v[4:5], 0, s[24:25]
	s_waitcnt vmcnt(62)
; DI void scan_item(const Params& p, int it) {
;     ...
;   for (int n0 = 0; n0 < NCHUNK; n0 += 26) {
;     float l[26], dd[26];
; #pragma unroll
;     for (int j = 0; j < 26; ++j) { l[j] = L[(size_t)(n0 + j) * 4096]; dd[j] = dc[(n0 + j) * 64]; }
; #pragma unroll
;     for (int j = 0; j < 26; ++j) { L[(size_t)(n0 + j) * 4096] = S; S = dd[j] * S + l[j]; }
;   }
	global_store_dword v[6:7], v52, off
	v_fmac_f32_e32 v53, s22, v52
	v_lshl_add_u64 v[6:7], v[6:7], 0, s[24:25]
	v_readlane_b32 s32, v65, 3
	global_load_dword v45, v[4:5], off
	v_lshl_add_u64 v[4:5], v[4:5], 0, s[24:25]
	s_waitcnt vmcnt(62)
	global_store_dword v[6:7], v53, off
	v_fmac_f32_e32 v54, s26, v53
	v_lshl_add_u64 v[6:7], v[6:7], 0, s[24:25]
	v_readlane_b32 s3, v65, 4
	global_load_dword v46, v[4:5], off
	v_lshl_add_u64 v[4:5], v[4:5], 0, s[24:25]
	s_waitcnt vmcnt(62)
	global_store_dword v[6:7], v54, off
	v_fmac_f32_e32 v55, s32, v54
	v_lshl_add_u64 v[6:7], v[6:7], 0, s[24:25]
	v_readlane_b32 s22, v65, 5
	global_load_dword v47, v[4:5], off
	v_lshl_add_u64 v[4:5], v[4:5], 0, s[24:25]
	s_waitcnt vmcnt(62)
	global_store_dword v[6:7], v55, off
	v_fmac_f32_e32 v56, s3, v55
	v_lshl_add_u64 v[6:7], v[6:7], 0, s[24:25]
	v_readlane_b32 s26, v65, 6
	global_load_dword v48, v[4:5], off
	v_lshl_add_u64 v[4:5], v[4:5], 0, s[24:25]
	s_waitcnt vmcnt(62)
	global_store_dword v[6:7], v56, off
	v_fmac_f32_e32 v57, s22, v56
	v_lshl_add_u64 v[6:7], v[6:7], 0, s[24:25]
	v_readlane_b32 s32, v65, 7
	global_load_dword v49, v[4:5], off
	v_lshl_add_u64 v[4:5], v[4:5], 0, s[24:25]
	s_waitcnt vmcnt(62)
	global_store_dword v[6:7], v57, off
	v_fmac_f32_e32 v58, s26, v57
	v_lshl_add_u64 v[6:7], v[6:7], 0, s[24:25]
	v_readlane_b32 s3, v65, 8
	global_load_dword v50, v[4:5], off
	v_lshl_add_u64 v[4:5], v[4:5], 0, s[24:25]
	s_waitcnt vmcnt(62)
	global_store_dword v[6:7], v58, off
	v_fmac_f32_e32 v59, s32, v58
	v_lshl_add_u64 v[6:7], v[6:7], 0, s[24:25]
	v_readlane_b32 s22, v65, 9
	global_load_dword v51, v[4:5], off
	v_lshl_add_u64 v[4:5], v[4:5], 0, s[24:25]
	s_waitcnt vmcnt(62)
	global_store_dword v[6:7], v59, off
	v_fmac_f32_e32 v20, s3, v59
	v_lshl_add_u64 v[6:7], v[6:7], 0, s[24:25]
	v_readlane_b32 s26, v65, 10
	global_load_dword v52, v[4:5], off
	v_lshl_add_u64 v[4:5], v[4:5], 0, s[24:25]
	s_waitcnt vmcnt(62)
	global_store_dword v[6:7], v20, off
	v_fmac_f32_e32 v21, s22, v20
	v_lshl_add_u64 v[6:7], v[6:7], 0, s[24:25]
	v_readlane_b32 s32, v65, 11
	global_load_dword v53, v[4:5], off
	v_lshl_add_u64 v[4:5], v[4:5], 0, s[24:25]
	s_waitcnt vmcnt(62)
	global_store_dword v[6:7], v21, off
	v_fmac_f32_e32 v22, s26, v21
	v_lshl_add_u64 v[6:7], v[6:7], 0, s[24:25]
	v_readlane_b32 s3, v65, 12
	global_load_dword v54, v[4:5], off
	v_lshl_add_u64 v[4:5], v[4:5], 0, s[24:25]
	s_waitcnt vmcnt(62)
	global_store_dword v[6:7], v22, off
	v_fmac_f32_e32 v23, s32, v22
	v_lshl_add_u64 v[6:7], v[6:7], 0, s[24:25]
	v_readlane_b32 s22, v65, 13
	global_load_dword v55, v[4:5], off
	v_lshl_add_u64 v[4:5], v[4:5], 0, s[24:25]
	s_waitcnt vmcnt(62)
	global_store_dword v[6:7], v23, off
	v_fmac_f32_e32 v24, s3, v23
	v_lshl_add_u64 v[6:7], v[6:7], 0, s[24:25]
	v_readlane_b32 s26, v65, 14
	global_load_dword v56, v[4:5], off
	v_lshl_add_u64 v[4:5], v[4:5], 0, s[24:25]
	s_waitcnt vmcnt(62)
	global_store_dword v[6:7], v24, off
	v_fmac_f32_e32 v25, s22, v24
	v_lshl_add_u64 v[6:7], v[6:7], 0, s[24:25]
	v_readlane_b32 s32, v65, 15
	global_load_dword v57, v[4:5], off
	v_lshl_add_u64 v[4:5], v[4:5], 0, s[24:25]
	s_waitcnt vmcnt(62)
	global_store_dword v[6:7], v25, off
	v_fmac_f32_e32 v26, s26, v25
	v_lshl_add_u64 v[6:7], v[6:7], 0, s[24:25]
	v_readlane_b32 s3, v65, 16
	global_load_dword v58, v[4:5], off
	v_lshl_add_u64 v[4:5], v[4:5], 0, s[24:25]
	s_waitcnt vmcnt(62)
	global_store_dword v[6:7], v26, off
	v_fmac_f32_e32 v27, s32, v26
	v_lshl_add_u64 v[6:7], v[6:7], 0, s[24:25]
	v_readlane_b32 s22, v65, 17
	global_load_dword v59, v[4:5], off
	v_lshl_add_u64 v[4:5], v[4:5], 0, s[24:25]
	s_waitcnt vmcnt(62)
	global_store_dword v[6:7], v27, off
	v_fmac_f32_e32 v28, s3, v27
	v_lshl_add_u64 v[6:7], v[6:7], 0, s[24:25]
	v_readlane_b32 s26, v65, 18
	global_load_dword v20, v[4:5], off
	v_lshl_add_u64 v[4:5], v[4:5], 0, s[24:25]
	s_waitcnt vmcnt(62)
	global_store_dword v[6:7], v28, off
	v_fmac_f32_e32 v29, s22, v28
	v_lshl_add_u64 v[6:7], v[6:7], 0, s[24:25]
	v_readlane_b32 s32, v65, 19
	global_load_dword v21, v[4:5], off
	v_lshl_add_u64 v[4:5], v[4:5], 0, s[24:25]
	s_waitcnt vmcnt(62)
	global_store_dword v[6:7], v29, off
	v_fmac_f32_e32 v30, s26, v29
	v_lshl_add_u64 v[6:7], v[6:7], 0, s[24:25]
	v_readlane_b32 s3, v65, 20
	global_load_dword v22, v[4:5], off
	v_lshl_add_u64 v[4:5], v[4:5], 0, s[24:25]
	s_waitcnt vmcnt(62)
	global_store_dword v[6:7], v30, off
	v_fmac_f32_e32 v31, s32, v30
	v_lshl_add_u64 v[6:7], v[6:7], 0, s[24:25]
	v_readlane_b32 s22, v65, 21
	global_load_dword v23, v[4:5], off
	v_lshl_add_u64 v[4:5], v[4:5], 0, s[24:25]
	s_waitcnt vmcnt(62)
	global_store_dword v[6:7], v31, off
	v_fmac_f32_e32 v32, s3, v31
	v_lshl_add_u64 v[6:7], v[6:7], 0, s[24:25]
	v_readlane_b32 s26, v65, 22
	global_load_dword v24, v[4:5], off
	v_lshl_add_u64 v[4:5], v[4:5], 0, s[24:25]
	s_waitcnt vmcnt(62)
	global_store_dword v[6:7], v32, off
	v_fmac_f32_e32 v33, s22, v32
	v_lshl_add_u64 v[6:7], v[6:7], 0, s[24:25]
	v_readlane_b32 s32, v65, 23
	global_load_dword v25, v[4:5], off
	v_lshl_add_u64 v[4:5], v[4:5], 0, s[24:25]
	s_waitcnt vmcnt(62)
	global_store_dword v[6:7], v33, off
	v_fmac_f32_e32 v34, s26, v33
	v_lshl_add_u64 v[6:7], v[6:7], 0, s[24:25]
	v_readlane_b32 s3, v65, 24
	global_load_dword v26, v[4:5], off
	v_lshl_add_u64 v[4:5], v[4:5], 0, s[24:25]
	s_waitcnt vmcnt(62)
	global_store_dword v[6:7], v34, off
	v_fmac_f32_e32 v35, s32, v34
	v_lshl_add_u64 v[6:7], v[6:7], 0, s[24:25]
	v_readlane_b32 s22, v65, 25
	global_load_dword v27, v[4:5], off
	v_lshl_add_u64 v[4:5], v[4:5], 0, s[24:25]
	s_waitcnt vmcnt(62)
; DI void scan_item(const Params& p, int it) {
;     ...
;   for (int n0 = 0; n0 < NCHUNK; n0 += 26) {
;     float l[26], dd[26];
; #pragma unroll
;     for (int j = 0; j < 26; ++j) { l[j] = L[(size_t)(n0 + j) * 4096]; dd[j] = dc[(n0 + j) * 64]; }
; #pragma unroll
;     for (int j = 0; j < 26; ++j) { L[(size_t)(n0 + j) * 4096] = S; S = dd[j] * S + l[j]; }
;   }
	global_store_dword v[6:7], v35, off
	v_fmac_f32_e32 v36, s3, v35
	v_lshl_add_u64 v[6:7], v[6:7], 0, s[24:25]
	v_readlane_b32 s26, v65, 26
	global_load_dword v28, v[4:5], off
	v_lshl_add_u64 v[4:5], v[4:5], 0, s[24:25]
	s_waitcnt vmcnt(62)
	global_store_dword v[6:7], v36, off
	v_fmac_f32_e32 v37, s22, v36
	v_lshl_add_u64 v[6:7], v[6:7], 0, s[24:25]
	v_readlane_b32 s32, v65, 27
	global_load_dword v29, v[4:5], off
	v_lshl_add_u64 v[4:5], v[4:5], 0, s[24:25]
	s_waitcnt vmcnt(62)
	global_store_dword v[6:7], v37, off
	v_fmac_f32_e32 v38, s26, v37
	v_lshl_add_u64 v[6:7], v[6:7], 0, s[24:25]
	v_readlane_b32 s3, v65, 28
	global_load_dword v30, v[4:5], off
	v_lshl_add_u64 v[4:5], v[4:5], 0, s[24:25]
	s_waitcnt vmcnt(62)
	global_store_dword v[6:7], v38, off
	v_fmac_f32_e32 v39, s32, v38
	v_lshl_add_u64 v[6:7], v[6:7], 0, s[24:25]
	v_readlane_b32 s22, v65, 29
	global_load_dword v31, v[4:5], off
	v_lshl_add_u64 v[4:5], v[4:5], 0, s[24:25]
	s_waitcnt vmcnt(62)
	global_store_dword v[6:7], v39, off
	v_fmac_f32_e32 v40, s3, v39
	v_lshl_add_u64 v[6:7], v[6:7], 0, s[24:25]
	v_readlane_b32 s26, v65, 30
	global_load_dword v32, v[4:5], off
	v_lshl_add_u64 v[4:5], v[4:5], 0, s[24:25]
	s_waitcnt vmcnt(62)
	global_store_dword v[6:7], v40, off
	v_fmac_f32_e32 v41, s22, v40
	v_lshl_add_u64 v[6:7], v[6:7], 0, s[24:25]
	v_readlane_b32 s32, v65, 31
	global_load_dword v33, v[4:5], off
	v_lshl_add_u64 v[4:5], v[4:5], 0, s[24:25]
	s_waitcnt vmcnt(62)
	global_store_dword v[6:7], v41, off
	v_fmac_f32_e32 v42, s26, v41
	v_lshl_add_u64 v[6:7], v[6:7], 0, s[24:25]
	v_readlane_b32 s3, v65, 32
	global_load_dword v34, v[4:5], off
	v_lshl_add_u64 v[4:5], v[4:5], 0, s[24:25]
	s_waitcnt vmcnt(62)
	global_store_dword v[6:7], v42, off
	v_fmac_f32_e32 v43, s32, v42
	v_lshl_add_u64 v[6:7], v[6:7], 0, s[24:25]
	v_readlane_b32 s22, v65, 33
	global_load_dword v35, v[4:5], off
	v_lshl_add_u64 v[4:5], v[4:5], 0, s[24:25]
	s_waitcnt vmcnt(62)
	global_store_dword v[6:7], v43, off
	v_fmac_f32_e32 v44, s3, v43
	v_lshl_add_u64 v[6:7], v[6:7], 0, s[24:25]
	v_readlane_b32 s26, v65, 34
	global_load_dword v36, v[4:5], off
	v_lshl_add_u64 v[4:5], v[4:5], 0, s[24:25]
	s_waitcnt vmcnt(62)
	global_store_dword v[6:7], v44, off
	v_fmac_f32_e32 v45, s22, v44
	v_lshl_add_u64 v[6:7], v[6:7], 0, s[24:25]
	v_readlane_b32 s32, v65, 35
	global_load_dword v37, v[4:5], off
	v_lshl_add_u64 v[4:5], v[4:5], 0, s[24:25]
	s_waitcnt vmcnt(62)
	global_store_dword v[6:7], v45, off
	v_fmac_f32_e32 v46, s26, v45
	v_lshl_add_u64 v[6:7], v[6:7], 0, s[24:25]
	v_readlane_b32 s3, v65, 36
	global_load_dword v38, v[4:5], off
	v_lshl_add_u64 v[4:5], v[4:5], 0, s[24:25]
	s_waitcnt vmcnt(62)
	global_store_dword v[6:7], v46, off
	v_fmac_f32_e32 v47, s32, v46
	v_lshl_add_u64 v[6:7], v[6:7], 0, s[24:25]
	v_readlane_b32 s22, v65, 37
	global_load_dword v39, v[4:5], off
	v_lshl_add_u64 v[4:5], v[4:5], 0, s[24:25]
	s_waitcnt vmcnt(62)
	global_store_dword v[6:7], v47, off
	v_fmac_f32_e32 v48, s3, v47
	v_lshl_add_u64 v[6:7], v[6:7], 0, s[24:25]
	v_readlane_b32 s26, v65, 38
	s_waitcnt vmcnt(61)
	global_store_dword v[6:7], v48, off
	v_fmac_f32_e32 v49, s22, v48
	v_lshl_add_u64 v[6:7], v[6:7], 0, s[24:25]
	v_readlane_b32 s32, v65, 39
	s_waitcnt vmcnt(60)
	global_store_dword v[6:7], v49, off
	v_fmac_f32_e32 v50, s26, v49
	v_lshl_add_u64 v[6:7], v[6:7], 0, s[24:25]
	v_readlane_b32 s3, v65, 40
	s_waitcnt vmcnt(59)
	global_store_dword v[6:7], v50, off
	v_fmac_f32_e32 v51, s32, v50
	v_lshl_add_u64 v[6:7], v[6:7], 0, s[24:25]
	v_readlane_b32 s22, v65, 41
	s_waitcnt vmcnt(58)
	global_store_dword v[6:7], v51, off
	v_fmac_f32_e32 v52, s3, v51
	v_lshl_add_u64 v[6:7], v[6:7], 0, s[24:25]
	v_readlane_b32 s26, v65, 42
	s_waitcnt vmcnt(57)
	global_store_dword v[6:7], v52, off
	v_fmac_f32_e32 v53, s22, v52
	v_lshl_add_u64 v[6:7], v[6:7], 0, s[24:25]
	v_readlane_b32 s32, v65, 43
	s_waitcnt vmcnt(56)
	global_store_dword v[6:7], v53, off
	v_fmac_f32_e32 v54, s26, v53
	v_lshl_add_u64 v[6:7], v[6:7], 0, s[24:25]
	v_readlane_b32 s3, v65, 44
	s_waitcnt vmcnt(55)
; DI void scan_item(const Params& p, int it) {
;     ...
;   for (int n0 = 0; n0 < NCHUNK; n0 += 26) {
;     float l[26], dd[26];
; #pragma unroll
;     for (int j = 0; j < 26; ++j) { l[j] = L[(size_t)(n0 + j) * 4096]; dd[j] = dc[(n0 + j) * 64]; }
; #pragma unroll
;     for (int j = 0; j < 26; ++j) { L[(size_t)(n0 + j) * 4096] = S; S = dd[j] * S + l[j]; }
;   }
	global_store_dword v[6:7], v54, off
	v_fmac_f32_e32 v55, s32, v54
	v_lshl_add_u64 v[6:7], v[6:7], 0, s[24:25]
	v_readlane_b32 s22, v65, 45
	s_waitcnt vmcnt(54)
	global_store_dword v[6:7], v55, off
	v_fmac_f32_e32 v56, s3, v55
	v_lshl_add_u64 v[6:7], v[6:7], 0, s[24:25]
	v_readlane_b32 s26, v65, 46
	s_waitcnt vmcnt(53)
	global_store_dword v[6:7], v56, off
	v_fmac_f32_e32 v57, s22, v56
	v_lshl_add_u64 v[6:7], v[6:7], 0, s[24:25]
	v_readlane_b32 s32, v65, 47
	s_waitcnt vmcnt(52)
	global_store_dword v[6:7], v57, off
	v_fmac_f32_e32 v58, s26, v57
	v_lshl_add_u64 v[6:7], v[6:7], 0, s[24:25]
	v_readlane_b32 s3, v65, 48
	s_waitcnt vmcnt(51)
	global_store_dword v[6:7], v58, off
	v_fmac_f32_e32 v59, s32, v58
	v_lshl_add_u64 v[6:7], v[6:7], 0, s[24:25]
	v_readlane_b32 s22, v65, 49
	s_waitcnt vmcnt(50)
	global_store_dword v[6:7], v59, off
	v_fmac_f32_e32 v20, s3, v59
	v_lshl_add_u64 v[6:7], v[6:7], 0, s[24:25]
	v_readlane_b32 s26, v65, 50
	s_waitcnt vmcnt(49)
	global_store_dword v[6:7], v20, off
	v_fmac_f32_e32 v21, s22, v20
	v_lshl_add_u64 v[6:7], v[6:7], 0, s[24:25]
	v_readlane_b32 s32, v65, 51
	s_waitcnt vmcnt(48)
	global_store_dword v[6:7], v21, off
	v_fmac_f32_e32 v22, s26, v21
	v_lshl_add_u64 v[6:7], v[6:7], 0, s[24:25]
	v_readlane_b32 s3, v65, 52
	s_waitcnt vmcnt(47)
	global_store_dword v[6:7], v22, off
	v_fmac_f32_e32 v23, s32, v22
	v_lshl_add_u64 v[6:7], v[6:7], 0, s[24:25]
	v_readlane_b32 s22, v65, 53
	s_waitcnt vmcnt(46)
	global_store_dword v[6:7], v23, off
	v_fmac_f32_e32 v24, s3, v23
	v_lshl_add_u64 v[6:7], v[6:7], 0, s[24:25]
	v_readlane_b32 s26, v65, 54
	s_waitcnt vmcnt(45)
	global_store_dword v[6:7], v24, off
	v_fmac_f32_e32 v25, s22, v24
	v_lshl_add_u64 v[6:7], v[6:7], 0, s[24:25]
	v_readlane_b32 s32, v65, 55
	s_waitcnt vmcnt(44)
	global_store_dword v[6:7], v25, off
	v_fmac_f32_e32 v26, s26, v25
	v_lshl_add_u64 v[6:7], v[6:7], 0, s[24:25]
	v_readlane_b32 s3, v65, 56
	s_waitcnt vmcnt(43)
	global_store_dword v[6:7], v26, off
	v_fmac_f32_e32 v27, s32, v26
	v_lshl_add_u64 v[6:7], v[6:7], 0, s[24:25]
	v_readlane_b32 s22, v65, 57
	s_waitcnt vmcnt(42)
	global_store_dword v[6:7], v27, off
	v_fmac_f32_e32 v28, s3, v27
	v_lshl_add_u64 v[6:7], v[6:7], 0, s[24:25]
	v_readlane_b32 s26, v65, 58
	s_waitcnt vmcnt(41)
	global_store_dword v[6:7], v28, off
	v_fmac_f32_e32 v29, s22, v28
	v_lshl_add_u64 v[6:7], v[6:7], 0, s[24:25]
	v_readlane_b32 s32, v65, 59
	s_waitcnt vmcnt(40)
	global_store_dword v[6:7], v29, off
	v_fmac_f32_e32 v30, s26, v29
	v_lshl_add_u64 v[6:7], v[6:7], 0, s[24:25]
	v_readlane_b32 s3, v65, 60
	s_waitcnt vmcnt(39)
	global_store_dword v[6:7], v30, off
	v_fmac_f32_e32 v31, s32, v30
	v_lshl_add_u64 v[6:7], v[6:7], 0, s[24:25]
	v_readlane_b32 s22, v65, 61
	s_waitcnt vmcnt(38)
	global_store_dword v[6:7], v31, off
	v_fmac_f32_e32 v32, s3, v31
	v_lshl_add_u64 v[6:7], v[6:7], 0, s[24:25]
	v_readlane_b32 s26, v65, 62
	s_waitcnt vmcnt(37)
	global_store_dword v[6:7], v32, off
	v_fmac_f32_e32 v33, s22, v32
	v_lshl_add_u64 v[6:7], v[6:7], 0, s[24:25]
	v_readlane_b32 s32, v65, 63
	s_waitcnt vmcnt(36)
	global_store_dword v[6:7], v33, off
	v_fmac_f32_e32 v34, s26, v33
	v_lshl_add_u64 v[6:7], v[6:7], 0, s[24:25]
	v_readlane_b32 s3, v66, 0
	s_waitcnt vmcnt(35)
	global_store_dword v[6:7], v34, off
	v_fmac_f32_e32 v35, s32, v34
	v_lshl_add_u64 v[6:7], v[6:7], 0, s[24:25]
	v_readlane_b32 s22, v66, 1
	s_waitcnt vmcnt(34)
	global_store_dword v[6:7], v35, off
	v_fmac_f32_e32 v36, s3, v35
	v_lshl_add_u64 v[6:7], v[6:7], 0, s[24:25]
	v_readlane_b32 s26, v66, 2
	s_waitcnt vmcnt(33)
	global_store_dword v[6:7], v36, off
	v_fmac_f32_e32 v37, s22, v36
	v_lshl_add_u64 v[6:7], v[6:7], 0, s[24:25]
	v_readlane_b32 s32, v66, 3
	s_waitcnt vmcnt(32)
	global_store_dword v[6:7], v37, off
	v_fmac_f32_e32 v38, s26, v37
	v_lshl_add_u64 v[6:7], v[6:7], 0, s[24:25]
	s_waitcnt vmcnt(31)
	global_store_dword v[6:7], v38, off
	v_fmac_f32_e32 v39, s32, v38
	v_lshl_add_u64 v[6:7], v[6:7], 0, s[24:25]
	s_waitcnt vmcnt(0)
	s_branch .LBB0_321
